# GEMM K-loops: no priority raise on the MFMA segments (all s_setprio replaced by s_nop 0, same code size)
# speedup vs baseline: 1.0119x; 1.0039x over previous
.LBB0_226:
	s_add_i32 vcc_lo, s82, 2
	s_add_u32 s20, s66, 0xffff0080
	s_addc_u32 s21, s67, -1
	s_add_i32 s52, 0, 0x10000
	s_cmp_eq_u32 s60, s82
	s_cselect_b32 s87, s39, s21
	s_cselect_b32 s86, s41, s20
	s_cselect_b32 s83, s88, s95
	s_cselect_b32 s82, s89, s94
	s_add_i32 s53, 0, 0x14000
	v_add_u32_e32 v154, s52, v140
	v_add_u32_e32 v170, s53, v140
	ds_read_b128 v[142:145], v154
	ds_read_b128 v[146:149], v154 offset:1024
	ds_read_b128 v[150:153], v154 offset:2048
	ds_read_b128 v[154:157], v154 offset:3072
	ds_read_b128 v[158:161], v170
	ds_read_b128 v[162:165], v170 offset:1024
	ds_read_b128 v[166:169], v170 offset:2048
	ds_read_b128 v[170:173], v170 offset:3072
	v_lshl_add_u64 v[186:187], s[66:67], 0, v[134:135]
	s_add_i32 m0, s13, 0xc000
	ds_read_b128 v[174:177], v141
	ds_read_b128 v[178:181], v141 offset:1024
	ds_read_b128 v[182:185], v141 offset:2048
	ds_read_b128 v[202:205], v141 offset:3072
	ds_read_b128 v[216:219], v141 offset:4096
	ds_read_b128 v[220:223], v141 offset:5120
	ds_read_b128 v[224:227], v141 offset:6144
	ds_read_b128 v[228:231], v141 offset:7168
	global_load_lds_dwordx4 v[186:187], off
	v_lshl_add_u64 v[186:187], s[66:67], 0, v[136:137]
	s_add_i32 m0, s13, 0xe000
	s_nop 0
	global_load_lds_dwordx4 v[186:187], off
	s_waitcnt vmcnt(8)
	s_waitcnt lgkmcnt(0)
	s_barrier
	s_nop 0
	s_waitcnt lgkmcnt(0)
	v_mfma_f32_16x16x32_bf16 v[120:123], v[142:145], v[174:177], v[120:123]
	v_mfma_f32_16x16x32_bf16 v[124:127], v[150:153], v[174:177], v[124:127]
	v_mfma_f32_16x16x32_bf16 v[108:111], v[142:145], v[182:185], v[108:111]
	v_mfma_f32_16x16x32_bf16 v[104:107], v[150:153], v[182:185], v[104:107]
	v_mfma_f32_16x16x32_bf16 v[92:95], v[142:145], v[216:219], v[92:95]
	v_mfma_f32_16x16x32_bf16 v[88:91], v[150:153], v[216:219], v[88:91]
	v_mfma_f32_16x16x32_bf16 v[76:79], v[142:145], v[224:227], v[76:79]
	v_mfma_f32_16x16x32_bf16 v[72:75], v[150:153], v[224:227], v[72:75]
	v_mfma_f32_16x16x32_bf16 v[120:123], v[146:149], v[178:181], v[120:123]
	v_mfma_f32_16x16x32_bf16 v[124:127], v[154:157], v[178:181], v[124:127]
	v_mfma_f32_16x16x32_bf16 v[108:111], v[146:149], v[202:205], v[108:111]
	v_mfma_f32_16x16x32_bf16 v[104:107], v[154:157], v[202:205], v[104:107]
	v_mfma_f32_16x16x32_bf16 v[92:95], v[146:149], v[220:223], v[92:95]
	v_mfma_f32_16x16x32_bf16 v[88:91], v[154:157], v[220:223], v[88:91]
	v_mfma_f32_16x16x32_bf16 v[76:79], v[146:149], v[228:231], v[76:79]
	v_mfma_f32_16x16x32_bf16 v[72:75], v[154:157], v[228:231], v[72:75]
	s_nop 0
	s_nop 0
	v_mfma_f32_16x16x32_bf16 v[116:119], v[158:161], v[174:177], v[116:119]
	v_mfma_f32_16x16x32_bf16 v[112:115], v[166:169], v[174:177], v[112:115]
	v_mfma_f32_16x16x32_bf16 v[100:103], v[158:161], v[182:185], v[100:103]
	v_mfma_f32_16x16x32_bf16 v[96:99], v[166:169], v[182:185], v[96:99]
	v_mfma_f32_16x16x32_bf16 v[84:87], v[158:161], v[216:219], v[84:87]
	v_mfma_f32_16x16x32_bf16 v[80:83], v[166:169], v[216:219], v[80:83]
	v_mfma_f32_16x16x32_bf16 v[68:71], v[158:161], v[224:227], v[68:71]
	v_mfma_f32_16x16x32_bf16 v[64:67], v[166:169], v[224:227], v[64:67]
	v_mfma_f32_16x16x32_bf16 v[116:119], v[162:165], v[178:181], v[116:119]
	v_mfma_f32_16x16x32_bf16 v[112:115], v[170:173], v[178:181], v[112:115]
	v_mfma_f32_16x16x32_bf16 v[100:103], v[162:165], v[202:205], v[100:103]
	v_mfma_f32_16x16x32_bf16 v[96:99], v[170:173], v[202:205], v[96:99]
	v_mfma_f32_16x16x32_bf16 v[84:87], v[162:165], v[220:223], v[84:87]
	v_mfma_f32_16x16x32_bf16 v[80:83], v[170:173], v[220:223], v[80:83]
	v_mfma_f32_16x16x32_bf16 v[68:71], v[162:165], v[228:231], v[68:71]
	v_mfma_f32_16x16x32_bf16 v[64:67], v[170:173], v[228:231], v[64:67]
	s_nop 0
	s_barrier
	s_add_i32 s20, s52, s12
	v_lshl_add_u64 v[186:187], s[82:83], 0, v[188:189]
	s_mov_b32 m0, s20
	ds_read_b128 v[174:177], v141 offset:16384
	ds_read_b128 v[178:181], v141 offset:17408
	ds_read_b128 v[182:185], v141 offset:18432
	ds_read_b128 v[202:205], v141 offset:19456
	ds_read_b128 v[216:219], v141 offset:20480
	ds_read_b128 v[220:223], v141 offset:21504
	ds_read_b128 v[224:227], v141 offset:22528
	ds_read_b128 v[228:231], v141 offset:23552
	global_load_lds_dwordx4 v[186:187], off
	s_add_i32 m0, s20, 0x2000
	s_add_u32 s20, s82, 0x10000
	v_lshl_add_u64 v[194:195], s[82:83], 0, v[128:129]
	s_addc_u32 s21, s83, 0
	s_add_i32 s52, s53, s12
	global_load_lds_dwordx4 v[194:195], off
	v_lshl_add_u64 v[196:197], s[20:21], 0, v[188:189]
	s_mov_b32 m0, s52
	v_lshl_add_u64 v[232:233], s[86:87], 0, v[130:131]
	global_load_lds_dwordx4 v[196:197], off
	v_lshl_add_u64 v[196:197], s[20:21], 0, v[128:129]
	s_add_i32 m0, s52, 0x2000
	s_nop 0
	global_load_lds_dwordx4 v[196:197], off
	v_lshl_add_u64 v[196:197], s[86:87], 0, v[132:133]
	s_mov_b32 m0, s13
	s_nop 0
	global_load_lds_dwordx4 v[196:197], off
	s_mov_b32 m0, s28
	s_nop 0
	global_load_lds_dwordx4 v[232:233], off
	s_waitcnt vmcnt(8)
	s_waitcnt lgkmcnt(0)
	s_barrier
	s_nop 0
	s_waitcnt lgkmcnt(0)
	v_mfma_f32_16x16x32_bf16 v[60:63], v[142:145], v[174:177], v[60:63]
	v_mfma_f32_16x16x32_bf16 v[56:59], v[150:153], v[174:177], v[56:59]
	v_mfma_f32_16x16x32_bf16 v[44:47], v[142:145], v[182:185], v[44:47]
	v_mfma_f32_16x16x32_bf16 v[40:43], v[150:153], v[182:185], v[40:43]
	v_mfma_f32_16x16x32_bf16 v[28:31], v[142:145], v[216:219], v[28:31]
	v_mfma_f32_16x16x32_bf16 v[24:27], v[150:153], v[216:219], v[24:27]
	v_mfma_f32_16x16x32_bf16 v[12:15], v[142:145], v[224:227], v[12:15]
	v_mfma_f32_16x16x32_bf16 v[8:11], v[150:153], v[224:227], v[8:11]
	v_mfma_f32_16x16x32_bf16 v[60:63], v[146:149], v[178:181], v[60:63]
	v_mfma_f32_16x16x32_bf16 v[56:59], v[154:157], v[178:181], v[56:59]
	v_mfma_f32_16x16x32_bf16 v[44:47], v[146:149], v[202:205], v[44:47]
	v_mfma_f32_16x16x32_bf16 v[40:43], v[154:157], v[202:205], v[40:43]
	v_mfma_f32_16x16x32_bf16 v[28:31], v[146:149], v[220:223], v[28:31]
	v_mfma_f32_16x16x32_bf16 v[24:27], v[154:157], v[220:223], v[24:27]
	v_mfma_f32_16x16x32_bf16 v[12:15], v[146:149], v[228:231], v[12:15]
	v_mfma_f32_16x16x32_bf16 v[8:11], v[154:157], v[228:231], v[8:11]
	s_nop 0
	s_nop 0
	v_mfma_f32_16x16x32_bf16 v[52:55], v[158:161], v[174:177], v[52:55]
	v_mfma_f32_16x16x32_bf16 v[48:51], v[166:169], v[174:177], v[48:51]
	v_mfma_f32_16x16x32_bf16 v[36:39], v[158:161], v[182:185], v[36:39]
	v_mfma_f32_16x16x32_bf16 v[32:35], v[166:169], v[182:185], v[32:35]
	v_mfma_f32_16x16x32_bf16 v[20:23], v[158:161], v[216:219], v[20:23]
	v_mfma_f32_16x16x32_bf16 v[16:19], v[166:169], v[216:219], v[16:19]
	v_mfma_f32_16x16x32_bf16 v[4:7], v[158:161], v[224:227], v[4:7]
	v_mfma_f32_16x16x32_bf16 v[0:3], v[166:169], v[224:227], v[0:3]
	v_mfma_f32_16x16x32_bf16 v[52:55], v[162:165], v[178:181], v[52:55]
	v_mfma_f32_16x16x32_bf16 v[48:51], v[170:173], v[178:181], v[48:51]
	v_mfma_f32_16x16x32_bf16 v[36:39], v[162:165], v[202:205], v[36:39]
	v_mfma_f32_16x16x32_bf16 v[32:35], v[170:173], v[202:205], v[32:35]
	v_mfma_f32_16x16x32_bf16 v[20:23], v[162:165], v[220:223], v[20:23]
	v_mfma_f32_16x16x32_bf16 v[16:19], v[170:173], v[220:223], v[16:19]
	v_mfma_f32_16x16x32_bf16 v[4:7], v[162:165], v[228:231], v[4:7]
	v_mfma_f32_16x16x32_bf16 v[0:3], v[170:173], v[228:231], v[0:3]
	s_nop 0
	s_barrier
	s_add_i32 s52, 0, 0x18000
	s_add_i32 s53, 0, 0x1c000
	v_add_u32_e32 v154, s52, v140
	v_add_u32_e32 v170, s53, v140
	ds_read_b128 v[142:145], v154
	ds_read_b128 v[146:149], v154 offset:1024
	ds_read_b128 v[150:153], v154 offset:2048
	ds_read_b128 v[154:157], v154 offset:3072
	ds_read_b128 v[158:161], v170
	ds_read_b128 v[162:165], v170 offset:1024
	ds_read_b128 v[166:169], v170 offset:2048
	ds_read_b128 v[170:173], v170 offset:3072
	s_add_u32 s20, s86, 0x10000
	s_addc_u32 s21, s87, 0
	s_mov_b32 m0, s46
	v_lshl_add_u64 v[234:235], s[20:21], 0, v[132:133]
	ds_read_b128 v[174:177], v141 offset:32768
	ds_read_b128 v[178:181], v141 offset:33792
	ds_read_b128 v[182:185], v141 offset:34816
	ds_read_b128 v[202:205], v141 offset:35840
	ds_read_b128 v[216:219], v141 offset:36864
	ds_read_b128 v[220:223], v141 offset:37888
	ds_read_b128 v[224:227], v141 offset:38912
	ds_read_b128 v[228:231], v141 offset:39936
	global_load_lds_dwordx4 v[234:235], off
	v_lshl_add_u64 v[234:235], s[20:21], 0, v[130:131]
	s_mov_b32 m0, s47
	s_nop 0
	global_load_lds_dwordx4 v[234:235], off
	s_waitcnt vmcnt(8)
	s_waitcnt lgkmcnt(0)
	s_barrier
	s_nop 0
	s_waitcnt lgkmcnt(0)
	v_mfma_f32_16x16x32_bf16 v[120:123], v[142:145], v[174:177], v[120:123]
	v_mfma_f32_16x16x32_bf16 v[124:127], v[150:153], v[174:177], v[124:127]
	v_mfma_f32_16x16x32_bf16 v[108:111], v[142:145], v[182:185], v[108:111]
	v_mfma_f32_16x16x32_bf16 v[104:107], v[150:153], v[182:185], v[104:107]
	v_mfma_f32_16x16x32_bf16 v[92:95], v[142:145], v[216:219], v[92:95]
	v_mfma_f32_16x16x32_bf16 v[88:91], v[150:153], v[216:219], v[88:91]
	v_mfma_f32_16x16x32_bf16 v[76:79], v[142:145], v[224:227], v[76:79]
	v_mfma_f32_16x16x32_bf16 v[72:75], v[150:153], v[224:227], v[72:75]
	v_mfma_f32_16x16x32_bf16 v[120:123], v[146:149], v[178:181], v[120:123]
	v_mfma_f32_16x16x32_bf16 v[124:127], v[154:157], v[178:181], v[124:127]
	v_mfma_f32_16x16x32_bf16 v[108:111], v[146:149], v[202:205], v[108:111]
	v_mfma_f32_16x16x32_bf16 v[104:107], v[154:157], v[202:205], v[104:107]
	v_mfma_f32_16x16x32_bf16 v[92:95], v[146:149], v[220:223], v[92:95]
	v_mfma_f32_16x16x32_bf16 v[88:91], v[154:157], v[220:223], v[88:91]
	v_mfma_f32_16x16x32_bf16 v[76:79], v[146:149], v[228:231], v[76:79]
	v_mfma_f32_16x16x32_bf16 v[72:75], v[154:157], v[228:231], v[72:75]
	s_nop 0
	s_nop 0
	v_mfma_f32_16x16x32_bf16 v[116:119], v[158:161], v[174:177], v[116:119]
	v_mfma_f32_16x16x32_bf16 v[112:115], v[166:169], v[174:177], v[112:115]
	v_mfma_f32_16x16x32_bf16 v[100:103], v[158:161], v[182:185], v[100:103]
	v_mfma_f32_16x16x32_bf16 v[96:99], v[166:169], v[182:185], v[96:99]
	v_mfma_f32_16x16x32_bf16 v[84:87], v[158:161], v[216:219], v[84:87]
	v_mfma_f32_16x16x32_bf16 v[80:83], v[166:169], v[216:219], v[80:83]
	v_mfma_f32_16x16x32_bf16 v[68:71], v[158:161], v[224:227], v[68:71]
	v_mfma_f32_16x16x32_bf16 v[64:67], v[166:169], v[224:227], v[64:67]
	v_mfma_f32_16x16x32_bf16 v[116:119], v[162:165], v[178:181], v[116:119]
	v_mfma_f32_16x16x32_bf16 v[112:115], v[170:173], v[178:181], v[112:115]
	v_mfma_f32_16x16x32_bf16 v[100:103], v[162:165], v[202:205], v[100:103]
	v_mfma_f32_16x16x32_bf16 v[96:99], v[170:173], v[202:205], v[96:99]
	v_mfma_f32_16x16x32_bf16 v[84:87], v[162:165], v[220:223], v[84:87]
	v_mfma_f32_16x16x32_bf16 v[80:83], v[170:173], v[220:223], v[80:83]
	v_mfma_f32_16x16x32_bf16 v[68:71], v[162:165], v[228:231], v[68:71]
	v_mfma_f32_16x16x32_bf16 v[64:67], v[170:173], v[228:231], v[64:67]
	s_nop 0
	s_barrier
	s_add_i32 s20, s52, s12
	v_lshl_add_u64 v[186:187], v[186:187], 0, s[62:63]
	s_mov_b32 m0, s20
	ds_read_b128 v[174:177], v141 offset:49152
	ds_read_b128 v[178:181], v141 offset:50176
	ds_read_b128 v[182:185], v141 offset:51200
	ds_read_b128 v[202:205], v141 offset:52224
	ds_read_b128 v[216:219], v141 offset:53248
	ds_read_b128 v[220:223], v141 offset:54272
	ds_read_b128 v[224:227], v141 offset:55296
	ds_read_b128 v[228:231], v141 offset:56320
	global_load_lds_dwordx4 v[186:187], off
	s_add_i32 m0, s20, 0x2000
	s_add_u32 s20, s82, 0x10080
	v_lshl_add_u64 v[186:187], v[194:195], 0, s[62:63]
	s_addc_u32 s21, s83, 0
	s_add_i32 s52, s53, s12
	global_load_lds_dwordx4 v[186:187], off
	v_lshl_add_u64 v[186:187], s[20:21], 0, v[188:189]
	s_mov_b32 m0, s52
	s_nop 0
	global_load_lds_dwordx4 v[186:187], off
	v_lshl_add_u64 v[186:187], s[20:21], 0, v[128:129]
	s_add_i32 m0, s52, 0x2000
	s_nop 0
	global_load_lds_dwordx4 v[186:187], off
	v_lshl_add_u64 v[186:187], v[196:197], 0, s[62:63]
	s_mov_b32 m0, s56
	s_nop 0
	global_load_lds_dwordx4 v[186:187], off
	v_lshl_add_u64 v[186:187], v[232:233], 0, s[62:63]
	s_mov_b32 m0, s57
	s_nop 0
	global_load_lds_dwordx4 v[186:187], off
	s_waitcnt vmcnt(8)
	s_waitcnt lgkmcnt(0)
	s_barrier
	s_nop 0
	s_waitcnt lgkmcnt(0)
	v_mfma_f32_16x16x32_bf16 v[60:63], v[142:145], v[174:177], v[60:63]
	v_mfma_f32_16x16x32_bf16 v[56:59], v[150:153], v[174:177], v[56:59]
	v_mfma_f32_16x16x32_bf16 v[44:47], v[142:145], v[182:185], v[44:47]
	v_mfma_f32_16x16x32_bf16 v[40:43], v[150:153], v[182:185], v[40:43]
	v_mfma_f32_16x16x32_bf16 v[28:31], v[142:145], v[216:219], v[28:31]
	v_mfma_f32_16x16x32_bf16 v[24:27], v[150:153], v[216:219], v[24:27]
	v_mfma_f32_16x16x32_bf16 v[12:15], v[142:145], v[224:227], v[12:15]
	v_mfma_f32_16x16x32_bf16 v[8:11], v[150:153], v[224:227], v[8:11]
	v_mfma_f32_16x16x32_bf16 v[60:63], v[146:149], v[178:181], v[60:63]
	v_mfma_f32_16x16x32_bf16 v[56:59], v[154:157], v[178:181], v[56:59]
	v_mfma_f32_16x16x32_bf16 v[44:47], v[146:149], v[202:205], v[44:47]
	v_mfma_f32_16x16x32_bf16 v[40:43], v[154:157], v[202:205], v[40:43]
	v_mfma_f32_16x16x32_bf16 v[28:31], v[146:149], v[220:223], v[28:31]
	v_mfma_f32_16x16x32_bf16 v[24:27], v[154:157], v[220:223], v[24:27]
	v_mfma_f32_16x16x32_bf16 v[12:15], v[146:149], v[228:231], v[12:15]
	v_mfma_f32_16x16x32_bf16 v[8:11], v[154:157], v[228:231], v[8:11]
	s_nop 0
	s_nop 0
	v_mfma_f32_16x16x32_bf16 v[52:55], v[158:161], v[174:177], v[52:55]
	v_mfma_f32_16x16x32_bf16 v[48:51], v[166:169], v[174:177], v[48:51]
	v_mfma_f32_16x16x32_bf16 v[36:39], v[158:161], v[182:185], v[36:39]
	v_mfma_f32_16x16x32_bf16 v[32:35], v[166:169], v[182:185], v[32:35]
	v_mfma_f32_16x16x32_bf16 v[20:23], v[158:161], v[216:219], v[20:23]
	v_mfma_f32_16x16x32_bf16 v[16:19], v[166:169], v[216:219], v[16:19]
	v_mfma_f32_16x16x32_bf16 v[4:7], v[158:161], v[224:227], v[4:7]
	v_mfma_f32_16x16x32_bf16 v[0:3], v[166:169], v[224:227], v[0:3]
	v_mfma_f32_16x16x32_bf16 v[52:55], v[162:165], v[178:181], v[52:55]
	v_mfma_f32_16x16x32_bf16 v[48:51], v[170:173], v[178:181], v[48:51]
	v_mfma_f32_16x16x32_bf16 v[36:39], v[162:165], v[202:205], v[36:39]
	v_mfma_f32_16x16x32_bf16 v[32:35], v[170:173], v[202:205], v[32:35]
	v_mfma_f32_16x16x32_bf16 v[20:23], v[162:165], v[220:223], v[20:23]
	v_mfma_f32_16x16x32_bf16 v[16:19], v[170:173], v[220:223], v[16:19]
	v_mfma_f32_16x16x32_bf16 v[4:7], v[162:165], v[228:231], v[4:7]
	v_mfma_f32_16x16x32_bf16 v[0:3], v[170:173], v[228:231], v[0:3]
	s_nop 0
	s_barrier
	s_add_u32 s66, s66, 0x100
	s_addc_u32 s67, s67, 0
	s_add_u32 s94, s94, 0x100
	s_addc_u32 s95, s95, 0
	s_cmp_ge_i32 vcc_lo, s48
	s_mov_b32 s82, vcc_lo
	s_cbranch_scc0 .LBB0_226
	s_mov_b64 s[88:89], 0x8000

.LBB0_247:
	s_add_i32 s61, s40, 2
	s_add_u32 s20, s38, 0xfffc0080
	s_addc_u32 s21, s39, -1
	s_add_i32 s52, 0, 0x10000
	s_cmp_eq_u32 s49, s40
	s_cselect_b32 s59, s35, s21
	s_cselect_b32 s58, s67, s20
	s_cselect_b32 s41, vcc_lo, s83
	s_cselect_b32 s40, vcc_hi, s82
	s_add_i32 s53, 0, 0x14000
	v_add_u32_e32 v148, s52, v168
	v_add_u32_e32 v164, s53, v168
	ds_read_b128 v[128:131], v148
	ds_read_b128 v[140:143], v148 offset:1024
	ds_read_b128 v[144:147], v148 offset:2048
	ds_read_b128 v[148:151], v148 offset:3072
	ds_read_b128 v[152:155], v164
	ds_read_b128 v[156:159], v164 offset:1024
	ds_read_b128 v[160:163], v164 offset:2048
	ds_read_b128 v[170:173], v164 offset:3072
	v_lshl_add_u64 v[164:165], s[38:39], 0, v[136:137]
	s_add_i32 m0, s46, 0xc000
	ds_read_b128 v[174:177], v169
	ds_read_b128 v[178:181], v169 offset:1024
	ds_read_b128 v[182:185], v169 offset:2048
	ds_read_b128 v[202:205], v169 offset:3072
	ds_read_b128 v[216:219], v169 offset:4096
	ds_read_b128 v[220:223], v169 offset:5120
	ds_read_b128 v[224:227], v169 offset:6144
	ds_read_b128 v[228:231], v169 offset:7168
	global_load_lds_dwordx4 v[164:165], off
	v_lshl_add_u64 v[164:165], s[38:39], 0, v[138:139]
	s_add_i32 m0, s46, 0xe000
	s_nop 0
	global_load_lds_dwordx4 v[164:165], off
	s_waitcnt vmcnt(8)
	s_waitcnt lgkmcnt(0)
	s_barrier
	s_nop 0
	s_waitcnt lgkmcnt(0)
	v_mfma_f32_16x16x32_bf16 v[120:123], v[128:131], v[174:177], v[120:123]
	v_mfma_f32_16x16x32_bf16 v[124:127], v[144:147], v[174:177], v[124:127]
	v_mfma_f32_16x16x32_bf16 v[108:111], v[128:131], v[182:185], v[108:111]
	v_mfma_f32_16x16x32_bf16 v[104:107], v[144:147], v[182:185], v[104:107]
	v_mfma_f32_16x16x32_bf16 v[92:95], v[128:131], v[216:219], v[92:95]
	v_mfma_f32_16x16x32_bf16 v[88:91], v[144:147], v[216:219], v[88:91]
	v_mfma_f32_16x16x32_bf16 v[76:79], v[128:131], v[224:227], v[76:79]
	v_mfma_f32_16x16x32_bf16 v[72:75], v[144:147], v[224:227], v[72:75]
	v_mfma_f32_16x16x32_bf16 v[120:123], v[140:143], v[178:181], v[120:123]
	v_mfma_f32_16x16x32_bf16 v[124:127], v[148:151], v[178:181], v[124:127]
	v_mfma_f32_16x16x32_bf16 v[108:111], v[140:143], v[202:205], v[108:111]
	v_mfma_f32_16x16x32_bf16 v[104:107], v[148:151], v[202:205], v[104:107]
	v_mfma_f32_16x16x32_bf16 v[92:95], v[140:143], v[220:223], v[92:95]
	v_mfma_f32_16x16x32_bf16 v[88:91], v[148:151], v[220:223], v[88:91]
	v_mfma_f32_16x16x32_bf16 v[76:79], v[140:143], v[228:231], v[76:79]
	v_mfma_f32_16x16x32_bf16 v[72:75], v[148:151], v[228:231], v[72:75]
	s_nop 0
	s_nop 0
	v_mfma_f32_16x16x32_bf16 v[116:119], v[152:155], v[174:177], v[116:119]
	v_mfma_f32_16x16x32_bf16 v[112:115], v[160:163], v[174:177], v[112:115]
	v_mfma_f32_16x16x32_bf16 v[100:103], v[152:155], v[182:185], v[100:103]
	v_mfma_f32_16x16x32_bf16 v[96:99], v[160:163], v[182:185], v[96:99]
	v_mfma_f32_16x16x32_bf16 v[84:87], v[152:155], v[216:219], v[84:87]
	v_mfma_f32_16x16x32_bf16 v[80:83], v[160:163], v[216:219], v[80:83]
	v_mfma_f32_16x16x32_bf16 v[68:71], v[152:155], v[224:227], v[68:71]
	v_mfma_f32_16x16x32_bf16 v[64:67], v[160:163], v[224:227], v[64:67]
	v_mfma_f32_16x16x32_bf16 v[116:119], v[156:159], v[178:181], v[116:119]
	v_mfma_f32_16x16x32_bf16 v[112:115], v[170:173], v[178:181], v[112:115]
	v_mfma_f32_16x16x32_bf16 v[100:103], v[156:159], v[202:205], v[100:103]
	v_mfma_f32_16x16x32_bf16 v[96:99], v[170:173], v[202:205], v[96:99]
	v_mfma_f32_16x16x32_bf16 v[84:87], v[156:159], v[220:223], v[84:87]
	v_mfma_f32_16x16x32_bf16 v[80:83], v[170:173], v[220:223], v[80:83]
	v_mfma_f32_16x16x32_bf16 v[68:71], v[156:159], v[228:231], v[68:71]
	v_mfma_f32_16x16x32_bf16 v[64:67], v[170:173], v[228:231], v[64:67]
	s_nop 0
	s_barrier
	s_add_i32 s20, s52, s55
	v_lshl_add_u64 v[164:165], s[40:41], 0, v[134:135]
	s_mov_b32 m0, s20
	ds_read_b128 v[174:177], v169 offset:16384
	ds_read_b128 v[178:181], v169 offset:17408
	ds_read_b128 v[182:185], v169 offset:18432
	ds_read_b128 v[202:205], v169 offset:19456
	ds_read_b128 v[216:219], v169 offset:20480
	ds_read_b128 v[220:223], v169 offset:21504
	ds_read_b128 v[224:227], v169 offset:22528
	ds_read_b128 v[228:231], v169 offset:23552
	global_load_lds_dwordx4 v[164:165], off
	s_add_i32 m0, s20, 0x2000
	s_add_u32 s20, s40, 0x40000
	v_lshl_add_u64 v[186:187], s[40:41], 0, v[132:133]
	s_addc_u32 s21, s41, 0
	s_add_i32 s52, s53, s55
	global_load_lds_dwordx4 v[186:187], off
	v_lshl_add_u64 v[194:195], s[20:21], 0, v[134:135]
	s_mov_b32 m0, s52
	v_lshl_add_u64 v[196:197], s[58:59], 0, v[132:133]
	global_load_lds_dwordx4 v[194:195], off
	v_lshl_add_u64 v[194:195], s[20:21], 0, v[132:133]
	s_add_i32 m0, s52, 0x2000
	s_nop 0
	global_load_lds_dwordx4 v[194:195], off
	v_lshl_add_u64 v[194:195], s[58:59], 0, v[134:135]
	s_mov_b32 m0, s46
	s_nop 0
	global_load_lds_dwordx4 v[194:195], off
	s_mov_b32 m0, s47
	s_nop 0
	global_load_lds_dwordx4 v[196:197], off
	s_waitcnt vmcnt(8)
	s_waitcnt lgkmcnt(0)
	s_barrier
	s_nop 0
	s_waitcnt lgkmcnt(0)
	v_mfma_f32_16x16x32_bf16 v[60:63], v[128:131], v[174:177], v[60:63]
	v_mfma_f32_16x16x32_bf16 v[56:59], v[144:147], v[174:177], v[56:59]
	v_mfma_f32_16x16x32_bf16 v[44:47], v[128:131], v[182:185], v[44:47]
	v_mfma_f32_16x16x32_bf16 v[40:43], v[144:147], v[182:185], v[40:43]
	v_mfma_f32_16x16x32_bf16 v[28:31], v[128:131], v[216:219], v[28:31]
	v_mfma_f32_16x16x32_bf16 v[24:27], v[144:147], v[216:219], v[24:27]
	v_mfma_f32_16x16x32_bf16 v[12:15], v[128:131], v[224:227], v[12:15]
	v_mfma_f32_16x16x32_bf16 v[8:11], v[144:147], v[224:227], v[8:11]
	v_mfma_f32_16x16x32_bf16 v[60:63], v[140:143], v[178:181], v[60:63]
	v_mfma_f32_16x16x32_bf16 v[56:59], v[148:151], v[178:181], v[56:59]
	v_mfma_f32_16x16x32_bf16 v[44:47], v[140:143], v[202:205], v[44:47]
	v_mfma_f32_16x16x32_bf16 v[40:43], v[148:151], v[202:205], v[40:43]
	v_mfma_f32_16x16x32_bf16 v[28:31], v[140:143], v[220:223], v[28:31]
	v_mfma_f32_16x16x32_bf16 v[24:27], v[148:151], v[220:223], v[24:27]
	v_mfma_f32_16x16x32_bf16 v[12:15], v[140:143], v[228:231], v[12:15]
	v_mfma_f32_16x16x32_bf16 v[8:11], v[148:151], v[228:231], v[8:11]
	s_nop 0
	s_nop 0
	v_mfma_f32_16x16x32_bf16 v[52:55], v[152:155], v[174:177], v[52:55]
	v_mfma_f32_16x16x32_bf16 v[48:51], v[160:163], v[174:177], v[48:51]
	v_mfma_f32_16x16x32_bf16 v[36:39], v[152:155], v[182:185], v[36:39]
	v_mfma_f32_16x16x32_bf16 v[32:35], v[160:163], v[182:185], v[32:35]
	v_mfma_f32_16x16x32_bf16 v[20:23], v[152:155], v[216:219], v[20:23]
	v_mfma_f32_16x16x32_bf16 v[16:19], v[160:163], v[216:219], v[16:19]
	v_mfma_f32_16x16x32_bf16 v[4:7], v[152:155], v[224:227], v[4:7]
	v_mfma_f32_16x16x32_bf16 v[0:3], v[160:163], v[224:227], v[0:3]
	v_mfma_f32_16x16x32_bf16 v[52:55], v[156:159], v[178:181], v[52:55]
	v_mfma_f32_16x16x32_bf16 v[48:51], v[170:173], v[178:181], v[48:51]
	v_mfma_f32_16x16x32_bf16 v[36:39], v[156:159], v[202:205], v[36:39]
	v_mfma_f32_16x16x32_bf16 v[32:35], v[170:173], v[202:205], v[32:35]
	v_mfma_f32_16x16x32_bf16 v[20:23], v[156:159], v[220:223], v[20:23]
	v_mfma_f32_16x16x32_bf16 v[16:19], v[170:173], v[220:223], v[16:19]
	v_mfma_f32_16x16x32_bf16 v[4:7], v[156:159], v[228:231], v[4:7]
	v_mfma_f32_16x16x32_bf16 v[0:3], v[170:173], v[228:231], v[0:3]
	s_nop 0
	s_barrier
	s_add_i32 s52, 0, 0x18000
	s_add_i32 s53, 0, 0x1c000
	v_add_u32_e32 v148, s52, v168
	v_add_u32_e32 v170, s53, v168
	ds_read_b128 v[128:131], v148
	ds_read_b128 v[140:143], v148 offset:1024
	ds_read_b128 v[144:147], v148 offset:2048
	ds_read_b128 v[148:151], v148 offset:3072
	ds_read_b128 v[152:155], v170
	ds_read_b128 v[156:159], v170 offset:1024
	ds_read_b128 v[160:163], v170 offset:2048
	ds_read_b128 v[170:173], v170 offset:3072
	s_add_u32 s20, s58, 0x40000
	s_addc_u32 s21, s59, 0
	s_mov_b32 m0, s25
	v_lshl_add_u64 v[232:233], s[20:21], 0, v[134:135]
	ds_read_b128 v[174:177], v169 offset:32768
	ds_read_b128 v[178:181], v169 offset:33792
	ds_read_b128 v[182:185], v169 offset:34816
	ds_read_b128 v[202:205], v169 offset:35840
	ds_read_b128 v[216:219], v169 offset:36864
	ds_read_b128 v[220:223], v169 offset:37888
	ds_read_b128 v[224:227], v169 offset:38912
	ds_read_b128 v[228:231], v169 offset:39936
	global_load_lds_dwordx4 v[232:233], off
	v_lshl_add_u64 v[232:233], s[20:21], 0, v[132:133]
	s_mov_b32 m0, s44
	s_nop 0
	global_load_lds_dwordx4 v[232:233], off
	s_waitcnt vmcnt(8)
	s_waitcnt lgkmcnt(0)
	s_barrier
	s_nop 0
	s_waitcnt lgkmcnt(0)
	v_mfma_f32_16x16x32_bf16 v[120:123], v[128:131], v[174:177], v[120:123]
	v_mfma_f32_16x16x32_bf16 v[124:127], v[144:147], v[174:177], v[124:127]
	v_mfma_f32_16x16x32_bf16 v[108:111], v[128:131], v[182:185], v[108:111]
	v_mfma_f32_16x16x32_bf16 v[104:107], v[144:147], v[182:185], v[104:107]
	v_mfma_f32_16x16x32_bf16 v[92:95], v[128:131], v[216:219], v[92:95]
	v_mfma_f32_16x16x32_bf16 v[88:91], v[144:147], v[216:219], v[88:91]
	v_mfma_f32_16x16x32_bf16 v[76:79], v[128:131], v[224:227], v[76:79]
	v_mfma_f32_16x16x32_bf16 v[72:75], v[144:147], v[224:227], v[72:75]
	v_mfma_f32_16x16x32_bf16 v[120:123], v[140:143], v[178:181], v[120:123]
	v_mfma_f32_16x16x32_bf16 v[124:127], v[148:151], v[178:181], v[124:127]
	v_mfma_f32_16x16x32_bf16 v[108:111], v[140:143], v[202:205], v[108:111]
	v_mfma_f32_16x16x32_bf16 v[104:107], v[148:151], v[202:205], v[104:107]
	v_mfma_f32_16x16x32_bf16 v[92:95], v[140:143], v[220:223], v[92:95]
	v_mfma_f32_16x16x32_bf16 v[88:91], v[148:151], v[220:223], v[88:91]
	v_mfma_f32_16x16x32_bf16 v[76:79], v[140:143], v[228:231], v[76:79]
	v_mfma_f32_16x16x32_bf16 v[72:75], v[148:151], v[228:231], v[72:75]
	s_nop 0
	s_nop 0
	v_mfma_f32_16x16x32_bf16 v[116:119], v[152:155], v[174:177], v[116:119]
	v_mfma_f32_16x16x32_bf16 v[112:115], v[160:163], v[174:177], v[112:115]
	v_mfma_f32_16x16x32_bf16 v[100:103], v[152:155], v[182:185], v[100:103]
	v_mfma_f32_16x16x32_bf16 v[96:99], v[160:163], v[182:185], v[96:99]
	v_mfma_f32_16x16x32_bf16 v[84:87], v[152:155], v[216:219], v[84:87]
	v_mfma_f32_16x16x32_bf16 v[80:83], v[160:163], v[216:219], v[80:83]
	v_mfma_f32_16x16x32_bf16 v[68:71], v[152:155], v[224:227], v[68:71]
	v_mfma_f32_16x16x32_bf16 v[64:67], v[160:163], v[224:227], v[64:67]
	v_mfma_f32_16x16x32_bf16 v[116:119], v[156:159], v[178:181], v[116:119]
	v_mfma_f32_16x16x32_bf16 v[112:115], v[170:173], v[178:181], v[112:115]
	v_mfma_f32_16x16x32_bf16 v[100:103], v[156:159], v[202:205], v[100:103]
	v_mfma_f32_16x16x32_bf16 v[96:99], v[170:173], v[202:205], v[96:99]
	v_mfma_f32_16x16x32_bf16 v[84:87], v[156:159], v[220:223], v[84:87]
	v_mfma_f32_16x16x32_bf16 v[80:83], v[170:173], v[220:223], v[80:83]
	v_mfma_f32_16x16x32_bf16 v[68:71], v[156:159], v[228:231], v[68:71]
	v_mfma_f32_16x16x32_bf16 v[64:67], v[170:173], v[228:231], v[64:67]
	s_nop 0
	s_barrier
	s_add_i32 s20, s52, s55
	v_lshl_add_u64 v[164:165], v[164:165], 0, s[62:63]
	s_mov_b32 m0, s20
	ds_read_b128 v[174:177], v169 offset:49152
	ds_read_b128 v[178:181], v169 offset:50176
	ds_read_b128 v[182:185], v169 offset:51200
	ds_read_b128 v[202:205], v169 offset:52224
	ds_read_b128 v[216:219], v169 offset:53248
	ds_read_b128 v[220:223], v169 offset:54272
	ds_read_b128 v[224:227], v169 offset:55296
	ds_read_b128 v[228:231], v169 offset:56320
	global_load_lds_dwordx4 v[164:165], off
	s_add_i32 m0, s20, 0x2000
	s_add_u32 s20, s40, 0x40080
	v_lshl_add_u64 v[164:165], v[186:187], 0, s[62:63]
	s_addc_u32 s21, s41, 0
	s_add_i32 s40, s53, s55
	global_load_lds_dwordx4 v[164:165], off
	v_lshl_add_u64 v[164:165], s[20:21], 0, v[134:135]
	s_mov_b32 m0, s40
	s_nop 0
	global_load_lds_dwordx4 v[164:165], off
	v_lshl_add_u64 v[164:165], s[20:21], 0, v[132:133]
	s_add_i32 m0, s40, 0x2000
	s_nop 0
	global_load_lds_dwordx4 v[164:165], off
	v_lshl_add_u64 v[164:165], v[194:195], 0, s[62:63]
	s_mov_b32 m0, s56
	s_nop 0
	global_load_lds_dwordx4 v[164:165], off
	v_lshl_add_u64 v[164:165], v[196:197], 0, s[62:63]
	s_mov_b32 m0, s57
	s_nop 0
	global_load_lds_dwordx4 v[164:165], off
	s_waitcnt vmcnt(8)
	s_waitcnt lgkmcnt(0)
	s_barrier
	s_nop 0
	s_waitcnt lgkmcnt(0)
	v_mfma_f32_16x16x32_bf16 v[60:63], v[128:131], v[174:177], v[60:63]
	v_mfma_f32_16x16x32_bf16 v[56:59], v[144:147], v[174:177], v[56:59]
	v_mfma_f32_16x16x32_bf16 v[44:47], v[128:131], v[182:185], v[44:47]
	v_mfma_f32_16x16x32_bf16 v[40:43], v[144:147], v[182:185], v[40:43]
	v_mfma_f32_16x16x32_bf16 v[28:31], v[128:131], v[216:219], v[28:31]
	v_mfma_f32_16x16x32_bf16 v[24:27], v[144:147], v[216:219], v[24:27]
	v_mfma_f32_16x16x32_bf16 v[12:15], v[128:131], v[224:227], v[12:15]
	v_mfma_f32_16x16x32_bf16 v[8:11], v[144:147], v[224:227], v[8:11]
	v_mfma_f32_16x16x32_bf16 v[60:63], v[140:143], v[178:181], v[60:63]
	v_mfma_f32_16x16x32_bf16 v[56:59], v[148:151], v[178:181], v[56:59]
	v_mfma_f32_16x16x32_bf16 v[44:47], v[140:143], v[202:205], v[44:47]
	v_mfma_f32_16x16x32_bf16 v[40:43], v[148:151], v[202:205], v[40:43]
	v_mfma_f32_16x16x32_bf16 v[28:31], v[140:143], v[220:223], v[28:31]
	v_mfma_f32_16x16x32_bf16 v[24:27], v[148:151], v[220:223], v[24:27]
	v_mfma_f32_16x16x32_bf16 v[12:15], v[140:143], v[228:231], v[12:15]
	v_mfma_f32_16x16x32_bf16 v[8:11], v[148:151], v[228:231], v[8:11]
	s_nop 0
	s_nop 0
	v_mfma_f32_16x16x32_bf16 v[52:55], v[152:155], v[174:177], v[52:55]
	v_mfma_f32_16x16x32_bf16 v[48:51], v[160:163], v[174:177], v[48:51]
	v_mfma_f32_16x16x32_bf16 v[36:39], v[152:155], v[182:185], v[36:39]
	v_mfma_f32_16x16x32_bf16 v[32:35], v[160:163], v[182:185], v[32:35]
	v_mfma_f32_16x16x32_bf16 v[20:23], v[152:155], v[216:219], v[20:23]
	v_mfma_f32_16x16x32_bf16 v[16:19], v[160:163], v[216:219], v[16:19]
	v_mfma_f32_16x16x32_bf16 v[4:7], v[152:155], v[224:227], v[4:7]
	v_mfma_f32_16x16x32_bf16 v[0:3], v[160:163], v[224:227], v[0:3]
	v_mfma_f32_16x16x32_bf16 v[52:55], v[156:159], v[178:181], v[52:55]
	v_mfma_f32_16x16x32_bf16 v[48:51], v[170:173], v[178:181], v[48:51]
	v_mfma_f32_16x16x32_bf16 v[36:39], v[156:159], v[202:205], v[36:39]
	v_mfma_f32_16x16x32_bf16 v[32:35], v[170:173], v[202:205], v[32:35]
	v_mfma_f32_16x16x32_bf16 v[20:23], v[156:159], v[220:223], v[20:23]
	v_mfma_f32_16x16x32_bf16 v[16:19], v[170:173], v[220:223], v[16:19]
	v_mfma_f32_16x16x32_bf16 v[4:7], v[156:159], v[228:231], v[4:7]
	v_mfma_f32_16x16x32_bf16 v[0:3], v[170:173], v[228:231], v[0:3]
	s_nop 0
	s_barrier
	s_add_u32 s38, s38, 0x100
	s_addc_u32 s39, s39, 0
	s_add_u32 s82, s82, 0x100
	s_addc_u32 s83, s83, 0
	s_cmp_ge_i32 s61, s80
	s_mov_b32 s40, s61
	s_cbranch_scc0 .LBB0_247

.LBB0_294:
	s_add_i32 vcc_lo, s82, 2
	s_add_u32 s20, s66, 0xfffc0080
	s_addc_u32 s21, s67, -1
	s_add_i32 vcc_hi, 0, 0x10000
	s_cmp_eq_u32 s60, s82
	s_cselect_b32 s87, s39, s21
	s_cselect_b32 s86, s41, s20
	v_add_u32_e32 v148, vcc_hi, v151
	s_cselect_b32 s83, s88, s95
	s_cselect_b32 s82, s89, s94
	s_add_i32 s52, 0, 0x14000
	ds_read_b128 v[140:143], v148
	ds_read_b128 v[144:147], v148 offset:1024
	ds_read_b128 v[154:157], v148 offset:2048
	ds_read_b128 v[158:161], v148 offset:3072
	v_add_u32_e32 v148, s52, v151
	ds_read_b128 v[162:165], v148
	ds_read_b128 v[166:169], v148 offset:1024
	ds_read_b128 v[170:173], v148 offset:2048
	ds_read_b128 v[174:177], v148 offset:3072
	v_lshl_add_u64 v[186:187], s[66:67], 0, v[136:137]
	s_add_i32 m0, s13, 0xc000
	ds_read_b128 v[178:181], v152
	ds_read_b128 v[182:185], v152 offset:1024
	ds_read_b128 v[202:205], v152 offset:2048
	ds_read_b128 v[216:219], v152 offset:3072
	ds_read_b128 v[220:223], v152 offset:4096
	ds_read_b128 v[224:227], v152 offset:5120
	ds_read_b128 v[228:231], v152 offset:6144
	ds_read_b128 v[232:235], v152 offset:7168
	global_load_lds_dwordx4 v[186:187], off
	v_lshl_add_u64 v[186:187], s[66:67], 0, v[138:139]
	s_add_i32 m0, s13, 0xe000
	s_nop 0
	global_load_lds_dwordx4 v[186:187], off
	s_waitcnt vmcnt(8)
	s_waitcnt lgkmcnt(0)
	s_barrier
	s_nop 0
	s_waitcnt lgkmcnt(0)
	v_mfma_f32_16x16x32_bf16 v[120:123], v[140:143], v[178:181], v[120:123]
	v_mfma_f32_16x16x32_bf16 v[124:127], v[154:157], v[178:181], v[124:127]
	v_mfma_f32_16x16x32_bf16 v[108:111], v[140:143], v[202:205], v[108:111]
	v_mfma_f32_16x16x32_bf16 v[104:107], v[154:157], v[202:205], v[104:107]
	v_mfma_f32_16x16x32_bf16 v[92:95], v[140:143], v[220:223], v[92:95]
	v_mfma_f32_16x16x32_bf16 v[88:91], v[154:157], v[220:223], v[88:91]
	v_mfma_f32_16x16x32_bf16 v[76:79], v[140:143], v[228:231], v[76:79]
	v_mfma_f32_16x16x32_bf16 v[72:75], v[154:157], v[228:231], v[72:75]
	v_mfma_f32_16x16x32_bf16 v[120:123], v[144:147], v[182:185], v[120:123]
	v_mfma_f32_16x16x32_bf16 v[124:127], v[158:161], v[182:185], v[124:127]
	v_mfma_f32_16x16x32_bf16 v[108:111], v[144:147], v[216:219], v[108:111]
	v_mfma_f32_16x16x32_bf16 v[104:107], v[158:161], v[216:219], v[104:107]
	v_mfma_f32_16x16x32_bf16 v[92:95], v[144:147], v[224:227], v[92:95]
	v_mfma_f32_16x16x32_bf16 v[88:91], v[158:161], v[224:227], v[88:91]
	v_mfma_f32_16x16x32_bf16 v[76:79], v[144:147], v[232:235], v[76:79]
	v_mfma_f32_16x16x32_bf16 v[72:75], v[158:161], v[232:235], v[72:75]
	s_nop 0
	s_nop 0
	v_mfma_f32_16x16x32_bf16 v[116:119], v[162:165], v[178:181], v[116:119]
	v_mfma_f32_16x16x32_bf16 v[112:115], v[170:173], v[178:181], v[112:115]
	v_mfma_f32_16x16x32_bf16 v[100:103], v[162:165], v[202:205], v[100:103]
	v_mfma_f32_16x16x32_bf16 v[96:99], v[170:173], v[202:205], v[96:99]
	v_mfma_f32_16x16x32_bf16 v[84:87], v[162:165], v[220:223], v[84:87]
	v_mfma_f32_16x16x32_bf16 v[80:83], v[170:173], v[220:223], v[80:83]
	v_mfma_f32_16x16x32_bf16 v[68:71], v[162:165], v[228:231], v[68:71]
	v_mfma_f32_16x16x32_bf16 v[64:67], v[170:173], v[228:231], v[64:67]
	v_mfma_f32_16x16x32_bf16 v[116:119], v[166:169], v[182:185], v[116:119]
	v_mfma_f32_16x16x32_bf16 v[112:115], v[174:177], v[182:185], v[112:115]
	v_mfma_f32_16x16x32_bf16 v[100:103], v[166:169], v[216:219], v[100:103]
	v_mfma_f32_16x16x32_bf16 v[96:99], v[174:177], v[216:219], v[96:99]
	v_mfma_f32_16x16x32_bf16 v[84:87], v[166:169], v[224:227], v[84:87]
	v_mfma_f32_16x16x32_bf16 v[80:83], v[174:177], v[224:227], v[80:83]
	v_mfma_f32_16x16x32_bf16 v[68:71], v[166:169], v[232:235], v[68:71]
	v_mfma_f32_16x16x32_bf16 v[64:67], v[174:177], v[232:235], v[64:67]
	s_nop 0
	s_barrier
	s_add_i32 s20, vcc_hi, s12
	v_lshl_add_u64 v[186:187], s[82:83], 0, v[132:133]
	s_mov_b32 m0, s20
	ds_read_b128 v[178:181], v152 offset:16384
	ds_read_b128 v[182:185], v152 offset:17408
	ds_read_b128 v[202:205], v152 offset:18432
	ds_read_b128 v[216:219], v152 offset:19456
	ds_read_b128 v[220:223], v152 offset:20480
	ds_read_b128 v[224:227], v152 offset:21504
	ds_read_b128 v[228:231], v152 offset:22528
	ds_read_b128 v[232:235], v152 offset:23552
	global_load_lds_dwordx4 v[186:187], off
	s_add_i32 m0, s20, 0x2000
	s_add_u32 s20, s82, 0x40000
	v_lshl_add_u64 v[194:195], s[82:83], 0, v[128:129]
	s_addc_u32 s21, s83, 0
	s_add_i32 s52, s52, s12
	global_load_lds_dwordx4 v[194:195], off
	v_lshl_add_u64 v[196:197], s[20:21], 0, v[132:133]
	s_mov_b32 m0, s52
	v_lshl_add_u64 v[236:237], s[86:87], 0, v[130:131]
	global_load_lds_dwordx4 v[196:197], off
	v_lshl_add_u64 v[196:197], s[20:21], 0, v[128:129]
	s_add_i32 m0, s52, 0x2000
	s_nop 0
	global_load_lds_dwordx4 v[196:197], off
	v_lshl_add_u64 v[196:197], s[86:87], 0, v[134:135]
	s_mov_b32 m0, s13
	s_nop 0
	global_load_lds_dwordx4 v[196:197], off
	s_mov_b32 m0, s28
	s_nop 0
	global_load_lds_dwordx4 v[236:237], off
	s_waitcnt vmcnt(8)
	s_waitcnt lgkmcnt(0)
	s_barrier
	s_nop 0
	s_waitcnt lgkmcnt(0)
	v_mfma_f32_16x16x32_bf16 v[60:63], v[140:143], v[178:181], v[60:63]
	v_mfma_f32_16x16x32_bf16 v[56:59], v[154:157], v[178:181], v[56:59]
	v_mfma_f32_16x16x32_bf16 v[44:47], v[140:143], v[202:205], v[44:47]
	v_mfma_f32_16x16x32_bf16 v[40:43], v[154:157], v[202:205], v[40:43]
	v_mfma_f32_16x16x32_bf16 v[28:31], v[140:143], v[220:223], v[28:31]
	v_mfma_f32_16x16x32_bf16 v[24:27], v[154:157], v[220:223], v[24:27]
	v_mfma_f32_16x16x32_bf16 v[12:15], v[140:143], v[228:231], v[12:15]
	v_mfma_f32_16x16x32_bf16 v[8:11], v[154:157], v[228:231], v[8:11]
	v_mfma_f32_16x16x32_bf16 v[60:63], v[144:147], v[182:185], v[60:63]
	v_mfma_f32_16x16x32_bf16 v[56:59], v[158:161], v[182:185], v[56:59]
	v_mfma_f32_16x16x32_bf16 v[44:47], v[144:147], v[216:219], v[44:47]
	v_mfma_f32_16x16x32_bf16 v[40:43], v[158:161], v[216:219], v[40:43]
	v_mfma_f32_16x16x32_bf16 v[28:31], v[144:147], v[224:227], v[28:31]
	v_mfma_f32_16x16x32_bf16 v[24:27], v[158:161], v[224:227], v[24:27]
	v_mfma_f32_16x16x32_bf16 v[12:15], v[144:147], v[232:235], v[12:15]
	v_mfma_f32_16x16x32_bf16 v[8:11], v[158:161], v[232:235], v[8:11]
	s_nop 0
	s_nop 0
	v_mfma_f32_16x16x32_bf16 v[52:55], v[162:165], v[178:181], v[52:55]
	v_mfma_f32_16x16x32_bf16 v[48:51], v[170:173], v[178:181], v[48:51]
	v_mfma_f32_16x16x32_bf16 v[36:39], v[162:165], v[202:205], v[36:39]
	v_mfma_f32_16x16x32_bf16 v[32:35], v[170:173], v[202:205], v[32:35]
	v_mfma_f32_16x16x32_bf16 v[20:23], v[162:165], v[220:223], v[20:23]
	v_mfma_f32_16x16x32_bf16 v[16:19], v[170:173], v[220:223], v[16:19]
	v_mfma_f32_16x16x32_bf16 v[4:7], v[162:165], v[228:231], v[4:7]
	v_mfma_f32_16x16x32_bf16 v[0:3], v[170:173], v[228:231], v[0:3]
	v_mfma_f32_16x16x32_bf16 v[52:55], v[166:169], v[182:185], v[52:55]
	v_mfma_f32_16x16x32_bf16 v[48:51], v[174:177], v[182:185], v[48:51]
	v_mfma_f32_16x16x32_bf16 v[36:39], v[166:169], v[216:219], v[36:39]
	v_mfma_f32_16x16x32_bf16 v[32:35], v[174:177], v[216:219], v[32:35]
	v_mfma_f32_16x16x32_bf16 v[20:23], v[166:169], v[224:227], v[20:23]
	v_mfma_f32_16x16x32_bf16 v[16:19], v[174:177], v[224:227], v[16:19]
	v_mfma_f32_16x16x32_bf16 v[4:7], v[166:169], v[232:235], v[4:7]
	v_mfma_f32_16x16x32_bf16 v[0:3], v[174:177], v[232:235], v[0:3]
	s_nop 0
	s_barrier
	s_add_i32 s52, 0, 0x18000
	v_add_u32_e32 v148, s52, v151
	s_add_i32 s53, 0, 0x1c000
	ds_read_b128 v[140:143], v148
	ds_read_b128 v[144:147], v148 offset:1024
	ds_read_b128 v[154:157], v148 offset:2048
	ds_read_b128 v[158:161], v148 offset:3072
	v_add_u32_e32 v148, s53, v151
	ds_read_b128 v[162:165], v148
	ds_read_b128 v[166:169], v148 offset:1024
	ds_read_b128 v[170:173], v148 offset:2048
	ds_read_b128 v[174:177], v148 offset:3072
	s_add_u32 s20, s86, 0x40000
	s_addc_u32 s21, s87, 0
	s_mov_b32 m0, s46
	v_lshl_add_u64 v[238:239], s[20:21], 0, v[134:135]
	ds_read_b128 v[178:181], v152 offset:32768
	ds_read_b128 v[182:185], v152 offset:33792
	ds_read_b128 v[202:205], v152 offset:34816
	ds_read_b128 v[216:219], v152 offset:35840
	ds_read_b128 v[220:223], v152 offset:36864
	ds_read_b128 v[224:227], v152 offset:37888
	ds_read_b128 v[228:231], v152 offset:38912
	ds_read_b128 v[232:235], v152 offset:39936
	global_load_lds_dwordx4 v[238:239], off
	v_lshl_add_u64 v[238:239], s[20:21], 0, v[130:131]
	s_mov_b32 m0, s47
	s_nop 0
	global_load_lds_dwordx4 v[238:239], off
	s_waitcnt vmcnt(8)
	s_waitcnt lgkmcnt(0)
	s_barrier
	s_nop 0
	s_waitcnt lgkmcnt(0)
	v_mfma_f32_16x16x32_bf16 v[120:123], v[140:143], v[178:181], v[120:123]
	v_mfma_f32_16x16x32_bf16 v[124:127], v[154:157], v[178:181], v[124:127]
	v_mfma_f32_16x16x32_bf16 v[108:111], v[140:143], v[202:205], v[108:111]
	v_mfma_f32_16x16x32_bf16 v[104:107], v[154:157], v[202:205], v[104:107]
	v_mfma_f32_16x16x32_bf16 v[92:95], v[140:143], v[220:223], v[92:95]
	v_mfma_f32_16x16x32_bf16 v[88:91], v[154:157], v[220:223], v[88:91]
	v_mfma_f32_16x16x32_bf16 v[76:79], v[140:143], v[228:231], v[76:79]
	v_mfma_f32_16x16x32_bf16 v[72:75], v[154:157], v[228:231], v[72:75]
	v_mfma_f32_16x16x32_bf16 v[120:123], v[144:147], v[182:185], v[120:123]
	v_mfma_f32_16x16x32_bf16 v[124:127], v[158:161], v[182:185], v[124:127]
	v_mfma_f32_16x16x32_bf16 v[108:111], v[144:147], v[216:219], v[108:111]
	v_mfma_f32_16x16x32_bf16 v[104:107], v[158:161], v[216:219], v[104:107]
	v_mfma_f32_16x16x32_bf16 v[92:95], v[144:147], v[224:227], v[92:95]
	v_mfma_f32_16x16x32_bf16 v[88:91], v[158:161], v[224:227], v[88:91]
	v_mfma_f32_16x16x32_bf16 v[76:79], v[144:147], v[232:235], v[76:79]
	v_mfma_f32_16x16x32_bf16 v[72:75], v[158:161], v[232:235], v[72:75]
	s_nop 0
	s_nop 0
	v_mfma_f32_16x16x32_bf16 v[116:119], v[162:165], v[178:181], v[116:119]
	v_mfma_f32_16x16x32_bf16 v[112:115], v[170:173], v[178:181], v[112:115]
	v_mfma_f32_16x16x32_bf16 v[100:103], v[162:165], v[202:205], v[100:103]
	v_mfma_f32_16x16x32_bf16 v[96:99], v[170:173], v[202:205], v[96:99]
	v_mfma_f32_16x16x32_bf16 v[84:87], v[162:165], v[220:223], v[84:87]
	v_mfma_f32_16x16x32_bf16 v[80:83], v[170:173], v[220:223], v[80:83]
	v_mfma_f32_16x16x32_bf16 v[68:71], v[162:165], v[228:231], v[68:71]
	v_mfma_f32_16x16x32_bf16 v[64:67], v[170:173], v[228:231], v[64:67]
	v_mfma_f32_16x16x32_bf16 v[116:119], v[166:169], v[182:185], v[116:119]
	v_mfma_f32_16x16x32_bf16 v[112:115], v[174:177], v[182:185], v[112:115]
	v_mfma_f32_16x16x32_bf16 v[100:103], v[166:169], v[216:219], v[100:103]
	v_mfma_f32_16x16x32_bf16 v[96:99], v[174:177], v[216:219], v[96:99]
	v_mfma_f32_16x16x32_bf16 v[84:87], v[166:169], v[224:227], v[84:87]
	v_mfma_f32_16x16x32_bf16 v[80:83], v[174:177], v[224:227], v[80:83]
	v_mfma_f32_16x16x32_bf16 v[68:71], v[166:169], v[232:235], v[68:71]
	v_mfma_f32_16x16x32_bf16 v[64:67], v[174:177], v[232:235], v[64:67]
	s_nop 0
	s_barrier
	s_add_i32 s20, s52, s12
	v_lshl_add_u64 v[186:187], v[186:187], 0, s[62:63]
	s_mov_b32 m0, s20
	ds_read_b128 v[178:181], v152 offset:49152
	ds_read_b128 v[182:185], v152 offset:50176
	ds_read_b128 v[202:205], v152 offset:51200
	ds_read_b128 v[216:219], v152 offset:52224
	ds_read_b128 v[220:223], v152 offset:53248
	ds_read_b128 v[224:227], v152 offset:54272
	ds_read_b128 v[228:231], v152 offset:55296
	ds_read_b128 v[232:235], v152 offset:56320
	global_load_lds_dwordx4 v[186:187], off
	s_add_i32 m0, s20, 0x2000
	s_add_u32 s20, s82, 0x40080
	v_lshl_add_u64 v[186:187], v[194:195], 0, s[62:63]
	s_addc_u32 s21, s83, 0
	s_add_i32 s52, s53, s12
	global_load_lds_dwordx4 v[186:187], off
	v_lshl_add_u64 v[186:187], s[20:21], 0, v[132:133]
	s_mov_b32 m0, s52
	s_nop 0
	global_load_lds_dwordx4 v[186:187], off
	v_lshl_add_u64 v[186:187], s[20:21], 0, v[128:129]
	s_add_i32 m0, s52, 0x2000
	s_nop 0
	global_load_lds_dwordx4 v[186:187], off
	v_lshl_add_u64 v[186:187], v[196:197], 0, s[62:63]
	s_mov_b32 m0, s48
	s_nop 0
	global_load_lds_dwordx4 v[186:187], off
	v_lshl_add_u64 v[186:187], v[236:237], 0, s[62:63]
	s_mov_b32 m0, s49
	s_nop 0
	global_load_lds_dwordx4 v[186:187], off
	s_waitcnt vmcnt(8)
	s_waitcnt lgkmcnt(0)
	s_barrier
	s_nop 0
	s_waitcnt lgkmcnt(0)
	v_mfma_f32_16x16x32_bf16 v[60:63], v[140:143], v[178:181], v[60:63]
	v_mfma_f32_16x16x32_bf16 v[56:59], v[154:157], v[178:181], v[56:59]
	v_mfma_f32_16x16x32_bf16 v[44:47], v[140:143], v[202:205], v[44:47]
	v_mfma_f32_16x16x32_bf16 v[40:43], v[154:157], v[202:205], v[40:43]
	v_mfma_f32_16x16x32_bf16 v[28:31], v[140:143], v[220:223], v[28:31]
	v_mfma_f32_16x16x32_bf16 v[24:27], v[154:157], v[220:223], v[24:27]
	v_mfma_f32_16x16x32_bf16 v[12:15], v[140:143], v[228:231], v[12:15]
	v_mfma_f32_16x16x32_bf16 v[8:11], v[154:157], v[228:231], v[8:11]
	v_mfma_f32_16x16x32_bf16 v[60:63], v[144:147], v[182:185], v[60:63]
	v_mfma_f32_16x16x32_bf16 v[56:59], v[158:161], v[182:185], v[56:59]
	v_mfma_f32_16x16x32_bf16 v[44:47], v[144:147], v[216:219], v[44:47]
	v_mfma_f32_16x16x32_bf16 v[40:43], v[158:161], v[216:219], v[40:43]
	v_mfma_f32_16x16x32_bf16 v[28:31], v[144:147], v[224:227], v[28:31]
	v_mfma_f32_16x16x32_bf16 v[24:27], v[158:161], v[224:227], v[24:27]
	v_mfma_f32_16x16x32_bf16 v[12:15], v[144:147], v[232:235], v[12:15]
	v_mfma_f32_16x16x32_bf16 v[8:11], v[158:161], v[232:235], v[8:11]
	s_nop 0
	s_nop 0
	v_mfma_f32_16x16x32_bf16 v[52:55], v[162:165], v[178:181], v[52:55]
	v_mfma_f32_16x16x32_bf16 v[48:51], v[170:173], v[178:181], v[48:51]
	v_mfma_f32_16x16x32_bf16 v[36:39], v[162:165], v[202:205], v[36:39]
	v_mfma_f32_16x16x32_bf16 v[32:35], v[170:173], v[202:205], v[32:35]
	v_mfma_f32_16x16x32_bf16 v[20:23], v[162:165], v[220:223], v[20:23]
	v_mfma_f32_16x16x32_bf16 v[16:19], v[170:173], v[220:223], v[16:19]
	v_mfma_f32_16x16x32_bf16 v[4:7], v[162:165], v[228:231], v[4:7]
	v_mfma_f32_16x16x32_bf16 v[0:3], v[170:173], v[228:231], v[0:3]
	v_mfma_f32_16x16x32_bf16 v[52:55], v[166:169], v[182:185], v[52:55]
	v_mfma_f32_16x16x32_bf16 v[48:51], v[174:177], v[182:185], v[48:51]
	v_mfma_f32_16x16x32_bf16 v[36:39], v[166:169], v[216:219], v[36:39]
	v_mfma_f32_16x16x32_bf16 v[32:35], v[174:177], v[216:219], v[32:35]
	v_mfma_f32_16x16x32_bf16 v[20:23], v[166:169], v[224:227], v[20:23]
	v_mfma_f32_16x16x32_bf16 v[16:19], v[174:177], v[224:227], v[16:19]
	v_mfma_f32_16x16x32_bf16 v[4:7], v[166:169], v[232:235], v[4:7]
	v_mfma_f32_16x16x32_bf16 v[0:3], v[174:177], v[232:235], v[0:3]
	s_nop 0
	s_barrier
	s_add_u32 s66, s66, 0x100
	s_addc_u32 s67, s67, 0
	s_add_u32 s94, s94, 0x100
	s_addc_u32 s95, s95, 0
	s_cmp_ge_i32 vcc_lo, s55
	s_mov_b32 s82, vcc_lo
	s_cbranch_scc0 .LBB0_294
	s_mov_b64 s[88:89], 0x8000

.LBB0_316:
	s_add_i32 vcc_lo, s82, 2
	s_add_u32 s20, s66, 0xfffc0080
	s_addc_u32 s21, s67, -1
	s_add_i32 s52, 0, 0x10000
	s_cmp_eq_u32 s60, s82
	s_cselect_b32 s87, s39, s21
	s_cselect_b32 s86, s41, s20
	s_cselect_b32 s83, s88, s95
	s_cselect_b32 s82, s89, s94
	s_add_i32 s53, 0, 0x14000
	v_add_u32_e32 v156, s52, v142
	v_add_u32_e32 v172, s53, v142
	ds_read_b128 v[144:147], v156
	ds_read_b128 v[148:151], v156 offset:1024
	ds_read_b128 v[152:155], v156 offset:2048
	ds_read_b128 v[156:159], v156 offset:3072
	ds_read_b128 v[160:163], v172
	ds_read_b128 v[164:167], v172 offset:1024
	ds_read_b128 v[168:171], v172 offset:2048
	ds_read_b128 v[172:175], v172 offset:3072
	v_lshl_add_u64 v[194:195], s[66:67], 0, v[136:137]
	s_add_i32 m0, s13, 0xc000
	ds_read_b128 v[176:179], v143
	ds_read_b128 v[180:183], v143 offset:1024
	ds_read_b128 v[184:187], v143 offset:2048
	ds_read_b128 v[202:205], v143 offset:3072
	ds_read_b128 v[216:219], v143 offset:4096
	ds_read_b128 v[220:223], v143 offset:5120
	ds_read_b128 v[224:227], v143 offset:6144
	ds_read_b128 v[228:231], v143 offset:7168
	global_load_lds_dwordx4 v[194:195], off
	v_lshl_add_u64 v[194:195], s[66:67], 0, v[138:139]
	s_add_i32 m0, s13, 0xe000
	s_nop 0
	global_load_lds_dwordx4 v[194:195], off
	s_waitcnt vmcnt(8)
	s_waitcnt lgkmcnt(0)
	s_barrier
	s_nop 0
	s_waitcnt lgkmcnt(0)
	v_mfma_f32_16x16x32_bf16 v[124:127], v[144:147], v[176:179], v[124:127]
	v_mfma_f32_16x16x32_bf16 v[120:123], v[152:155], v[176:179], v[120:123]
	v_mfma_f32_16x16x32_bf16 v[108:111], v[144:147], v[184:187], v[108:111]
	v_mfma_f32_16x16x32_bf16 v[104:107], v[152:155], v[184:187], v[104:107]
	v_mfma_f32_16x16x32_bf16 v[92:95], v[144:147], v[216:219], v[92:95]
	v_mfma_f32_16x16x32_bf16 v[88:91], v[152:155], v[216:219], v[88:91]
	v_mfma_f32_16x16x32_bf16 v[76:79], v[144:147], v[224:227], v[76:79]
	v_mfma_f32_16x16x32_bf16 v[72:75], v[152:155], v[224:227], v[72:75]
	v_mfma_f32_16x16x32_bf16 v[124:127], v[148:151], v[180:183], v[124:127]
	v_mfma_f32_16x16x32_bf16 v[120:123], v[156:159], v[180:183], v[120:123]
	v_mfma_f32_16x16x32_bf16 v[108:111], v[148:151], v[202:205], v[108:111]
	v_mfma_f32_16x16x32_bf16 v[104:107], v[156:159], v[202:205], v[104:107]
	v_mfma_f32_16x16x32_bf16 v[92:95], v[148:151], v[220:223], v[92:95]
	v_mfma_f32_16x16x32_bf16 v[88:91], v[156:159], v[220:223], v[88:91]
	v_mfma_f32_16x16x32_bf16 v[76:79], v[148:151], v[228:231], v[76:79]
	v_mfma_f32_16x16x32_bf16 v[72:75], v[156:159], v[228:231], v[72:75]
	s_nop 0
	s_nop 0
	v_mfma_f32_16x16x32_bf16 v[116:119], v[160:163], v[176:179], v[116:119]
	v_mfma_f32_16x16x32_bf16 v[112:115], v[168:171], v[176:179], v[112:115]
	v_mfma_f32_16x16x32_bf16 v[100:103], v[160:163], v[184:187], v[100:103]
	v_mfma_f32_16x16x32_bf16 v[96:99], v[168:171], v[184:187], v[96:99]
	v_mfma_f32_16x16x32_bf16 v[84:87], v[160:163], v[216:219], v[84:87]
	v_mfma_f32_16x16x32_bf16 v[80:83], v[168:171], v[216:219], v[80:83]
	v_mfma_f32_16x16x32_bf16 v[68:71], v[160:163], v[224:227], v[68:71]
	v_mfma_f32_16x16x32_bf16 v[64:67], v[168:171], v[224:227], v[64:67]
	v_mfma_f32_16x16x32_bf16 v[116:119], v[164:167], v[180:183], v[116:119]
	v_mfma_f32_16x16x32_bf16 v[112:115], v[172:175], v[180:183], v[112:115]
	v_mfma_f32_16x16x32_bf16 v[100:103], v[164:167], v[202:205], v[100:103]
	v_mfma_f32_16x16x32_bf16 v[96:99], v[172:175], v[202:205], v[96:99]
	v_mfma_f32_16x16x32_bf16 v[84:87], v[164:167], v[220:223], v[84:87]
	v_mfma_f32_16x16x32_bf16 v[80:83], v[172:175], v[220:223], v[80:83]
	v_mfma_f32_16x16x32_bf16 v[68:71], v[164:167], v[228:231], v[68:71]
	v_mfma_f32_16x16x32_bf16 v[64:67], v[172:175], v[228:231], v[64:67]
	s_nop 0
	s_barrier
	s_add_i32 s20, s52, s12
	v_lshl_add_u64 v[194:195], s[82:83], 0, v[132:133]
	s_mov_b32 m0, s20
	ds_read_b128 v[176:179], v143 offset:16384
	ds_read_b128 v[180:183], v143 offset:17408
	ds_read_b128 v[184:187], v143 offset:18432
	ds_read_b128 v[202:205], v143 offset:19456
	ds_read_b128 v[216:219], v143 offset:20480
	ds_read_b128 v[220:223], v143 offset:21504
	ds_read_b128 v[224:227], v143 offset:22528
	ds_read_b128 v[228:231], v143 offset:23552
	global_load_lds_dwordx4 v[194:195], off
	s_add_i32 m0, s20, 0x2000
	s_add_u32 s20, s82, 0x40000
	v_lshl_add_u64 v[196:197], s[82:83], 0, v[128:129]
	s_addc_u32 s21, s83, 0
	s_add_i32 s52, s53, s12
	global_load_lds_dwordx4 v[196:197], off
	v_lshl_add_u64 v[232:233], s[20:21], 0, v[132:133]
	s_mov_b32 m0, s52
	v_lshl_add_u64 v[234:235], s[86:87], 0, v[130:131]
	global_load_lds_dwordx4 v[232:233], off
	v_lshl_add_u64 v[232:233], s[20:21], 0, v[128:129]
	s_add_i32 m0, s52, 0x2000
	s_nop 0
	global_load_lds_dwordx4 v[232:233], off
	v_lshl_add_u64 v[232:233], s[86:87], 0, v[134:135]
	s_mov_b32 m0, s13
	s_nop 0
	global_load_lds_dwordx4 v[232:233], off
	s_mov_b32 m0, s28
	s_nop 0
	global_load_lds_dwordx4 v[234:235], off
	s_waitcnt vmcnt(8)
	s_waitcnt lgkmcnt(0)
	s_barrier
	s_nop 0
	s_waitcnt lgkmcnt(0)
	v_mfma_f32_16x16x32_bf16 v[60:63], v[144:147], v[176:179], v[60:63]
	v_mfma_f32_16x16x32_bf16 v[56:59], v[152:155], v[176:179], v[56:59]
	v_mfma_f32_16x16x32_bf16 v[44:47], v[144:147], v[184:187], v[44:47]
	v_mfma_f32_16x16x32_bf16 v[40:43], v[152:155], v[184:187], v[40:43]
	v_mfma_f32_16x16x32_bf16 v[28:31], v[144:147], v[216:219], v[28:31]
	v_mfma_f32_16x16x32_bf16 v[24:27], v[152:155], v[216:219], v[24:27]
	v_mfma_f32_16x16x32_bf16 v[12:15], v[144:147], v[224:227], v[12:15]
	v_mfma_f32_16x16x32_bf16 v[8:11], v[152:155], v[224:227], v[8:11]
	v_mfma_f32_16x16x32_bf16 v[60:63], v[148:151], v[180:183], v[60:63]
	v_mfma_f32_16x16x32_bf16 v[56:59], v[156:159], v[180:183], v[56:59]
	v_mfma_f32_16x16x32_bf16 v[44:47], v[148:151], v[202:205], v[44:47]
	v_mfma_f32_16x16x32_bf16 v[40:43], v[156:159], v[202:205], v[40:43]
	v_mfma_f32_16x16x32_bf16 v[28:31], v[148:151], v[220:223], v[28:31]
	v_mfma_f32_16x16x32_bf16 v[24:27], v[156:159], v[220:223], v[24:27]
	v_mfma_f32_16x16x32_bf16 v[12:15], v[148:151], v[228:231], v[12:15]
	v_mfma_f32_16x16x32_bf16 v[8:11], v[156:159], v[228:231], v[8:11]
	s_nop 0
	s_nop 0
	v_mfma_f32_16x16x32_bf16 v[52:55], v[160:163], v[176:179], v[52:55]
	v_mfma_f32_16x16x32_bf16 v[48:51], v[168:171], v[176:179], v[48:51]
	v_mfma_f32_16x16x32_bf16 v[36:39], v[160:163], v[184:187], v[36:39]
	v_mfma_f32_16x16x32_bf16 v[32:35], v[168:171], v[184:187], v[32:35]
	v_mfma_f32_16x16x32_bf16 v[20:23], v[160:163], v[216:219], v[20:23]
	v_mfma_f32_16x16x32_bf16 v[16:19], v[168:171], v[216:219], v[16:19]
	v_mfma_f32_16x16x32_bf16 v[4:7], v[160:163], v[224:227], v[4:7]
	v_mfma_f32_16x16x32_bf16 v[0:3], v[168:171], v[224:227], v[0:3]
	v_mfma_f32_16x16x32_bf16 v[52:55], v[164:167], v[180:183], v[52:55]
	v_mfma_f32_16x16x32_bf16 v[48:51], v[172:175], v[180:183], v[48:51]
	v_mfma_f32_16x16x32_bf16 v[36:39], v[164:167], v[202:205], v[36:39]
	v_mfma_f32_16x16x32_bf16 v[32:35], v[172:175], v[202:205], v[32:35]
	v_mfma_f32_16x16x32_bf16 v[20:23], v[164:167], v[220:223], v[20:23]
	v_mfma_f32_16x16x32_bf16 v[16:19], v[172:175], v[220:223], v[16:19]
	v_mfma_f32_16x16x32_bf16 v[4:7], v[164:167], v[228:231], v[4:7]
	v_mfma_f32_16x16x32_bf16 v[0:3], v[172:175], v[228:231], v[0:3]
	s_nop 0
	s_barrier
	s_add_i32 s52, 0, 0x18000
	s_add_i32 s53, 0, 0x1c000
	v_add_u32_e32 v156, s52, v142
	v_add_u32_e32 v172, s53, v142
	ds_read_b128 v[144:147], v156
	ds_read_b128 v[148:151], v156 offset:1024
	ds_read_b128 v[152:155], v156 offset:2048
	ds_read_b128 v[156:159], v156 offset:3072
	ds_read_b128 v[160:163], v172
	ds_read_b128 v[164:167], v172 offset:1024
	ds_read_b128 v[168:171], v172 offset:2048
	ds_read_b128 v[172:175], v172 offset:3072
	s_add_u32 s20, s86, 0x40000
	s_addc_u32 s21, s87, 0
	s_mov_b32 m0, s46
	v_lshl_add_u64 v[236:237], s[20:21], 0, v[134:135]
	ds_read_b128 v[176:179], v143 offset:32768
	ds_read_b128 v[180:183], v143 offset:33792
	ds_read_b128 v[184:187], v143 offset:34816
	ds_read_b128 v[202:205], v143 offset:35840
	ds_read_b128 v[216:219], v143 offset:36864
	ds_read_b128 v[220:223], v143 offset:37888
	ds_read_b128 v[224:227], v143 offset:38912
	ds_read_b128 v[228:231], v143 offset:39936
	global_load_lds_dwordx4 v[236:237], off
	v_lshl_add_u64 v[236:237], s[20:21], 0, v[130:131]
	s_mov_b32 m0, s47
	s_nop 0
	global_load_lds_dwordx4 v[236:237], off
	s_waitcnt vmcnt(8)
	s_waitcnt lgkmcnt(0)
	s_barrier
	s_nop 0
	s_waitcnt lgkmcnt(0)
	v_mfma_f32_16x16x32_bf16 v[124:127], v[144:147], v[176:179], v[124:127]
	v_mfma_f32_16x16x32_bf16 v[120:123], v[152:155], v[176:179], v[120:123]
	v_mfma_f32_16x16x32_bf16 v[108:111], v[144:147], v[184:187], v[108:111]
	v_mfma_f32_16x16x32_bf16 v[104:107], v[152:155], v[184:187], v[104:107]
	v_mfma_f32_16x16x32_bf16 v[92:95], v[144:147], v[216:219], v[92:95]
	v_mfma_f32_16x16x32_bf16 v[88:91], v[152:155], v[216:219], v[88:91]
	v_mfma_f32_16x16x32_bf16 v[76:79], v[144:147], v[224:227], v[76:79]
	v_mfma_f32_16x16x32_bf16 v[72:75], v[152:155], v[224:227], v[72:75]
	v_mfma_f32_16x16x32_bf16 v[124:127], v[148:151], v[180:183], v[124:127]
	v_mfma_f32_16x16x32_bf16 v[120:123], v[156:159], v[180:183], v[120:123]
	v_mfma_f32_16x16x32_bf16 v[108:111], v[148:151], v[202:205], v[108:111]
	v_mfma_f32_16x16x32_bf16 v[104:107], v[156:159], v[202:205], v[104:107]
	v_mfma_f32_16x16x32_bf16 v[92:95], v[148:151], v[220:223], v[92:95]
	v_mfma_f32_16x16x32_bf16 v[88:91], v[156:159], v[220:223], v[88:91]
	v_mfma_f32_16x16x32_bf16 v[76:79], v[148:151], v[228:231], v[76:79]
	v_mfma_f32_16x16x32_bf16 v[72:75], v[156:159], v[228:231], v[72:75]
	s_nop 0
	s_nop 0
	v_mfma_f32_16x16x32_bf16 v[116:119], v[160:163], v[176:179], v[116:119]
	v_mfma_f32_16x16x32_bf16 v[112:115], v[168:171], v[176:179], v[112:115]
	v_mfma_f32_16x16x32_bf16 v[100:103], v[160:163], v[184:187], v[100:103]
	v_mfma_f32_16x16x32_bf16 v[96:99], v[168:171], v[184:187], v[96:99]
	v_mfma_f32_16x16x32_bf16 v[84:87], v[160:163], v[216:219], v[84:87]
	v_mfma_f32_16x16x32_bf16 v[80:83], v[168:171], v[216:219], v[80:83]
	v_mfma_f32_16x16x32_bf16 v[68:71], v[160:163], v[224:227], v[68:71]
	v_mfma_f32_16x16x32_bf16 v[64:67], v[168:171], v[224:227], v[64:67]
	v_mfma_f32_16x16x32_bf16 v[116:119], v[164:167], v[180:183], v[116:119]
	v_mfma_f32_16x16x32_bf16 v[112:115], v[172:175], v[180:183], v[112:115]
	v_mfma_f32_16x16x32_bf16 v[100:103], v[164:167], v[202:205], v[100:103]
	v_mfma_f32_16x16x32_bf16 v[96:99], v[172:175], v[202:205], v[96:99]
	v_mfma_f32_16x16x32_bf16 v[84:87], v[164:167], v[220:223], v[84:87]
	v_mfma_f32_16x16x32_bf16 v[80:83], v[172:175], v[220:223], v[80:83]
	v_mfma_f32_16x16x32_bf16 v[68:71], v[164:167], v[228:231], v[68:71]
	v_mfma_f32_16x16x32_bf16 v[64:67], v[172:175], v[228:231], v[64:67]
	s_nop 0
	s_barrier
	s_add_i32 s20, s52, s12
	v_lshl_add_u64 v[194:195], v[194:195], 0, s[62:63]
	s_mov_b32 m0, s20
	ds_read_b128 v[176:179], v143 offset:49152
	ds_read_b128 v[180:183], v143 offset:50176
	ds_read_b128 v[184:187], v143 offset:51200
	ds_read_b128 v[202:205], v143 offset:52224
	ds_read_b128 v[216:219], v143 offset:53248
	ds_read_b128 v[220:223], v143 offset:54272
	ds_read_b128 v[224:227], v143 offset:55296
	ds_read_b128 v[228:231], v143 offset:56320
	global_load_lds_dwordx4 v[194:195], off
	s_add_i32 m0, s20, 0x2000
	s_add_u32 s20, s82, 0x40080
	v_lshl_add_u64 v[194:195], v[196:197], 0, s[62:63]
	s_addc_u32 s21, s83, 0
	s_add_i32 s52, s53, s12
	global_load_lds_dwordx4 v[194:195], off
	v_lshl_add_u64 v[194:195], s[20:21], 0, v[132:133]
	s_mov_b32 m0, s52
	s_nop 0
	global_load_lds_dwordx4 v[194:195], off
	v_lshl_add_u64 v[194:195], s[20:21], 0, v[128:129]
	s_add_i32 m0, s52, 0x2000
	s_nop 0
	global_load_lds_dwordx4 v[194:195], off
	v_lshl_add_u64 v[194:195], v[232:233], 0, s[62:63]
	s_mov_b32 m0, s56
	s_nop 0
	global_load_lds_dwordx4 v[194:195], off
	v_lshl_add_u64 v[194:195], v[234:235], 0, s[62:63]
	s_mov_b32 m0, s57
	s_nop 0
	global_load_lds_dwordx4 v[194:195], off
	s_waitcnt vmcnt(8)
	s_waitcnt lgkmcnt(0)
	s_barrier
	s_nop 0
	s_waitcnt lgkmcnt(0)
	v_mfma_f32_16x16x32_bf16 v[60:63], v[144:147], v[176:179], v[60:63]
	v_mfma_f32_16x16x32_bf16 v[56:59], v[152:155], v[176:179], v[56:59]
	v_mfma_f32_16x16x32_bf16 v[44:47], v[144:147], v[184:187], v[44:47]
	v_mfma_f32_16x16x32_bf16 v[40:43], v[152:155], v[184:187], v[40:43]
	v_mfma_f32_16x16x32_bf16 v[28:31], v[144:147], v[216:219], v[28:31]
	v_mfma_f32_16x16x32_bf16 v[24:27], v[152:155], v[216:219], v[24:27]
	v_mfma_f32_16x16x32_bf16 v[12:15], v[144:147], v[224:227], v[12:15]
	v_mfma_f32_16x16x32_bf16 v[8:11], v[152:155], v[224:227], v[8:11]
	v_mfma_f32_16x16x32_bf16 v[60:63], v[148:151], v[180:183], v[60:63]
	v_mfma_f32_16x16x32_bf16 v[56:59], v[156:159], v[180:183], v[56:59]
	v_mfma_f32_16x16x32_bf16 v[44:47], v[148:151], v[202:205], v[44:47]
	v_mfma_f32_16x16x32_bf16 v[40:43], v[156:159], v[202:205], v[40:43]
	v_mfma_f32_16x16x32_bf16 v[28:31], v[148:151], v[220:223], v[28:31]
	v_mfma_f32_16x16x32_bf16 v[24:27], v[156:159], v[220:223], v[24:27]
	v_mfma_f32_16x16x32_bf16 v[12:15], v[148:151], v[228:231], v[12:15]
	v_mfma_f32_16x16x32_bf16 v[8:11], v[156:159], v[228:231], v[8:11]
	s_nop 0
	s_nop 0
	v_mfma_f32_16x16x32_bf16 v[52:55], v[160:163], v[176:179], v[52:55]
	v_mfma_f32_16x16x32_bf16 v[48:51], v[168:171], v[176:179], v[48:51]
	v_mfma_f32_16x16x32_bf16 v[36:39], v[160:163], v[184:187], v[36:39]
	v_mfma_f32_16x16x32_bf16 v[32:35], v[168:171], v[184:187], v[32:35]
	v_mfma_f32_16x16x32_bf16 v[20:23], v[160:163], v[216:219], v[20:23]
	v_mfma_f32_16x16x32_bf16 v[16:19], v[168:171], v[216:219], v[16:19]
	v_mfma_f32_16x16x32_bf16 v[4:7], v[160:163], v[224:227], v[4:7]
	v_mfma_f32_16x16x32_bf16 v[0:3], v[168:171], v[224:227], v[0:3]
	v_mfma_f32_16x16x32_bf16 v[52:55], v[164:167], v[180:183], v[52:55]
	v_mfma_f32_16x16x32_bf16 v[48:51], v[172:175], v[180:183], v[48:51]
	v_mfma_f32_16x16x32_bf16 v[36:39], v[164:167], v[202:205], v[36:39]
	v_mfma_f32_16x16x32_bf16 v[32:35], v[172:175], v[202:205], v[32:35]
	v_mfma_f32_16x16x32_bf16 v[20:23], v[164:167], v[220:223], v[20:23]
	v_mfma_f32_16x16x32_bf16 v[16:19], v[172:175], v[220:223], v[16:19]
	v_mfma_f32_16x16x32_bf16 v[4:7], v[164:167], v[228:231], v[4:7]
	v_mfma_f32_16x16x32_bf16 v[0:3], v[172:175], v[228:231], v[0:3]
	s_nop 0
	s_barrier
	s_add_u32 s66, s66, 0x100
	s_addc_u32 s67, s67, 0
	s_add_u32 s94, s94, 0x100
	s_addc_u32 s95, s95, 0
	s_cmp_ge_i32 vcc_lo, s48
	s_mov_b32 s82, vcc_lo
	s_cbranch_scc0 .LBB0_316
	s_mov_b64 s[88:89], 0x8000

.LBB0_578:
	s_add_i32 s95, s42, 2
	s_add_u32 s43, s40, 0xfffc0080
	s_addc_u32 s56, s41, -1
	s_add_i32 vcc_lo, 0, 0x10000
	s_cmp_eq_u32 s87, s42
	s_cselect_b32 s57, s49, s56
	s_cselect_b32 s56, s51, s43
	s_cselect_b32 s43, s59, s94
	s_cselect_b32 s42, s88, s89
	s_add_i32 s36, 0, 0x14000
	v_add_u32_e32 v150, vcc_lo, v156
	v_add_u32_e32 v170, s36, v156
	ds_read_b128 v[128:131], v150
	ds_read_b128 v[132:135], v150 offset:1024
	ds_read_b128 v[146:149], v150 offset:2048
	ds_read_b128 v[150:153], v150 offset:3072
	ds_read_b128 v[158:161], v170
	ds_read_b128 v[162:165], v170 offset:1024
	ds_read_b128 v[166:169], v170 offset:2048
	ds_read_b128 v[170:173], v170 offset:3072
	v_lshl_add_u64 v[186:187], s[40:41], 0, v[142:143]
	s_add_i32 m0, s5, 0xc000
	ds_read_b128 v[174:177], v157
	ds_read_b128 v[178:181], v157 offset:1024
	ds_read_b128 v[182:185], v157 offset:2048
	ds_read_b128 v[194:197], v157 offset:3072
	ds_read_b128 v[202:205], v157 offset:4096
	ds_read_b128 v[216:219], v157 offset:5120
	ds_read_b128 v[220:223], v157 offset:6144
	ds_read_b128 v[224:227], v157 offset:7168
	global_load_lds_dwordx4 v[186:187], off
	v_lshl_add_u64 v[186:187], s[40:41], 0, v[144:145]
	s_add_i32 m0, s5, 0xe000
	s_nop 0
	global_load_lds_dwordx4 v[186:187], off
	s_waitcnt vmcnt(8)
	s_waitcnt lgkmcnt(0)
	s_barrier
	s_nop 0
	s_waitcnt lgkmcnt(0)
	v_mfma_f32_16x16x32_bf16 v[124:127], v[128:131], v[174:177], v[124:127]
	v_mfma_f32_16x16x32_bf16 v[120:123], v[146:149], v[174:177], v[120:123]
	v_mfma_f32_16x16x32_bf16 v[108:111], v[128:131], v[182:185], v[108:111]
	v_mfma_f32_16x16x32_bf16 v[104:107], v[146:149], v[182:185], v[104:107]
	v_mfma_f32_16x16x32_bf16 v[92:95], v[128:131], v[202:205], v[92:95]
	v_mfma_f32_16x16x32_bf16 v[88:91], v[146:149], v[202:205], v[88:91]
	v_mfma_f32_16x16x32_bf16 v[76:79], v[128:131], v[220:223], v[76:79]
	v_mfma_f32_16x16x32_bf16 v[72:75], v[146:149], v[220:223], v[72:75]
	v_mfma_f32_16x16x32_bf16 v[124:127], v[132:135], v[178:181], v[124:127]
	v_mfma_f32_16x16x32_bf16 v[120:123], v[150:153], v[178:181], v[120:123]
	v_mfma_f32_16x16x32_bf16 v[108:111], v[132:135], v[194:197], v[108:111]
	v_mfma_f32_16x16x32_bf16 v[104:107], v[150:153], v[194:197], v[104:107]
	v_mfma_f32_16x16x32_bf16 v[92:95], v[132:135], v[216:219], v[92:95]
	v_mfma_f32_16x16x32_bf16 v[88:91], v[150:153], v[216:219], v[88:91]
	v_mfma_f32_16x16x32_bf16 v[76:79], v[132:135], v[224:227], v[76:79]
	v_mfma_f32_16x16x32_bf16 v[72:75], v[150:153], v[224:227], v[72:75]
	s_nop 0
	s_nop 0
	v_mfma_f32_16x16x32_bf16 v[116:119], v[158:161], v[174:177], v[116:119]
	v_mfma_f32_16x16x32_bf16 v[112:115], v[166:169], v[174:177], v[112:115]
	v_mfma_f32_16x16x32_bf16 v[100:103], v[158:161], v[182:185], v[100:103]
	v_mfma_f32_16x16x32_bf16 v[96:99], v[166:169], v[182:185], v[96:99]
	v_mfma_f32_16x16x32_bf16 v[84:87], v[158:161], v[202:205], v[84:87]
	v_mfma_f32_16x16x32_bf16 v[80:83], v[166:169], v[202:205], v[80:83]
	v_mfma_f32_16x16x32_bf16 v[68:71], v[158:161], v[220:223], v[68:71]
	v_mfma_f32_16x16x32_bf16 v[64:67], v[166:169], v[220:223], v[64:67]
	v_mfma_f32_16x16x32_bf16 v[116:119], v[162:165], v[178:181], v[116:119]
	v_mfma_f32_16x16x32_bf16 v[112:115], v[170:173], v[178:181], v[112:115]
	v_mfma_f32_16x16x32_bf16 v[100:103], v[162:165], v[194:197], v[100:103]
	v_mfma_f32_16x16x32_bf16 v[96:99], v[170:173], v[194:197], v[96:99]
	v_mfma_f32_16x16x32_bf16 v[84:87], v[162:165], v[216:219], v[84:87]
	v_mfma_f32_16x16x32_bf16 v[80:83], v[170:173], v[216:219], v[80:83]
	v_mfma_f32_16x16x32_bf16 v[68:71], v[162:165], v[224:227], v[68:71]
	v_mfma_f32_16x16x32_bf16 v[64:67], v[170:173], v[224:227], v[64:67]
	s_nop 0
	s_barrier
	s_add_i32 s37, vcc_lo, s60
	v_lshl_add_u64 v[186:187], s[42:43], 0, v[188:189]
	s_mov_b32 m0, s37
	ds_read_b128 v[174:177], v157 offset:16384
	ds_read_b128 v[178:181], v157 offset:17408
	ds_read_b128 v[182:185], v157 offset:18432
	ds_read_b128 v[194:197], v157 offset:19456
	ds_read_b128 v[202:205], v157 offset:20480
	ds_read_b128 v[216:219], v157 offset:21504
	ds_read_b128 v[220:223], v157 offset:22528
	ds_read_b128 v[224:227], v157 offset:23552
	global_load_lds_dwordx4 v[186:187], off
	s_add_i32 m0, s37, 0x2000
	s_add_u32 vcc_lo, s42, 0x40000
	v_lshl_add_u64 v[228:229], s[42:43], 0, v[136:137]
	s_addc_u32 vcc_hi, s43, 0
	s_add_i32 s36, s36, s60
	global_load_lds_dwordx4 v[228:229], off
	v_lshl_add_u64 v[230:231], vcc, 0, v[188:189]
	s_mov_b32 m0, s36
	v_lshl_add_u64 v[232:233], s[56:57], 0, v[138:139]
	global_load_lds_dwordx4 v[230:231], off
	v_lshl_add_u64 v[230:231], vcc, 0, v[136:137]
	s_add_i32 m0, s36, 0x2000
	s_nop 0
	global_load_lds_dwordx4 v[230:231], off
	v_lshl_add_u64 v[230:231], s[56:57], 0, v[140:141]
	s_mov_b32 m0, s5
	s_nop 0
	global_load_lds_dwordx4 v[230:231], off
	s_mov_b32 m0, s6
	s_nop 0
	global_load_lds_dwordx4 v[232:233], off
	s_waitcnt vmcnt(8)
	s_waitcnt lgkmcnt(0)
	s_barrier
	s_nop 0
	s_waitcnt lgkmcnt(0)
	v_mfma_f32_16x16x32_bf16 v[60:63], v[128:131], v[174:177], v[60:63]
	v_mfma_f32_16x16x32_bf16 v[56:59], v[146:149], v[174:177], v[56:59]
	v_mfma_f32_16x16x32_bf16 v[44:47], v[128:131], v[182:185], v[44:47]
	v_mfma_f32_16x16x32_bf16 v[40:43], v[146:149], v[182:185], v[40:43]
	v_mfma_f32_16x16x32_bf16 v[28:31], v[128:131], v[202:205], v[28:31]
	v_mfma_f32_16x16x32_bf16 v[24:27], v[146:149], v[202:205], v[24:27]
	v_mfma_f32_16x16x32_bf16 v[12:15], v[128:131], v[220:223], v[12:15]
	v_mfma_f32_16x16x32_bf16 v[8:11], v[146:149], v[220:223], v[8:11]
	v_mfma_f32_16x16x32_bf16 v[60:63], v[132:135], v[178:181], v[60:63]
	v_mfma_f32_16x16x32_bf16 v[56:59], v[150:153], v[178:181], v[56:59]
	v_mfma_f32_16x16x32_bf16 v[44:47], v[132:135], v[194:197], v[44:47]
	v_mfma_f32_16x16x32_bf16 v[40:43], v[150:153], v[194:197], v[40:43]
	v_mfma_f32_16x16x32_bf16 v[28:31], v[132:135], v[216:219], v[28:31]
	v_mfma_f32_16x16x32_bf16 v[24:27], v[150:153], v[216:219], v[24:27]
	v_mfma_f32_16x16x32_bf16 v[12:15], v[132:135], v[224:227], v[12:15]
	v_mfma_f32_16x16x32_bf16 v[8:11], v[150:153], v[224:227], v[8:11]
	s_nop 0
	s_nop 0
	v_mfma_f32_16x16x32_bf16 v[52:55], v[158:161], v[174:177], v[52:55]
	v_mfma_f32_16x16x32_bf16 v[48:51], v[166:169], v[174:177], v[48:51]
	v_mfma_f32_16x16x32_bf16 v[36:39], v[158:161], v[182:185], v[36:39]
	v_mfma_f32_16x16x32_bf16 v[32:35], v[166:169], v[182:185], v[32:35]
	v_mfma_f32_16x16x32_bf16 v[20:23], v[158:161], v[202:205], v[20:23]
	v_mfma_f32_16x16x32_bf16 v[16:19], v[166:169], v[202:205], v[16:19]
	v_mfma_f32_16x16x32_bf16 v[4:7], v[158:161], v[220:223], v[4:7]
	v_mfma_f32_16x16x32_bf16 v[0:3], v[166:169], v[220:223], v[0:3]
	v_mfma_f32_16x16x32_bf16 v[52:55], v[162:165], v[178:181], v[52:55]
	v_mfma_f32_16x16x32_bf16 v[48:51], v[170:173], v[178:181], v[48:51]
	v_mfma_f32_16x16x32_bf16 v[36:39], v[162:165], v[194:197], v[36:39]
	v_mfma_f32_16x16x32_bf16 v[32:35], v[170:173], v[194:197], v[32:35]
	v_mfma_f32_16x16x32_bf16 v[20:23], v[162:165], v[216:219], v[20:23]
	v_mfma_f32_16x16x32_bf16 v[16:19], v[170:173], v[216:219], v[16:19]
	v_mfma_f32_16x16x32_bf16 v[4:7], v[162:165], v[224:227], v[4:7]
	v_mfma_f32_16x16x32_bf16 v[0:3], v[170:173], v[224:227], v[0:3]
	s_nop 0
	s_barrier
	s_add_i32 s36, 0, 0x18000
	s_add_i32 s37, 0, 0x1c000
	v_add_u32_e32 v150, s36, v156
	v_add_u32_e32 v170, s37, v156
	ds_read_b128 v[128:131], v150
	ds_read_b128 v[132:135], v150 offset:1024
	ds_read_b128 v[146:149], v150 offset:2048
	ds_read_b128 v[150:153], v150 offset:3072
	ds_read_b128 v[158:161], v170
	ds_read_b128 v[162:165], v170 offset:1024
	ds_read_b128 v[166:169], v170 offset:2048
	ds_read_b128 v[170:173], v170 offset:3072
	s_add_u32 s56, s56, 0x40000
	s_addc_u32 s57, s57, 0
	s_mov_b32 m0, s7
	v_lshl_add_u64 v[234:235], s[56:57], 0, v[140:141]
	ds_read_b128 v[174:177], v157 offset:32768
	ds_read_b128 v[178:181], v157 offset:33792
	ds_read_b128 v[182:185], v157 offset:34816
	ds_read_b128 v[194:197], v157 offset:35840
	ds_read_b128 v[202:205], v157 offset:36864
	ds_read_b128 v[216:219], v157 offset:37888
	ds_read_b128 v[220:223], v157 offset:38912
	ds_read_b128 v[224:227], v157 offset:39936
	global_load_lds_dwordx4 v[234:235], off
	v_lshl_add_u64 v[234:235], s[56:57], 0, v[138:139]
	s_mov_b32 m0, s8
	s_nop 0
	global_load_lds_dwordx4 v[234:235], off
	s_waitcnt vmcnt(8)
	s_waitcnt lgkmcnt(0)
	s_barrier
	s_nop 0
	s_waitcnt lgkmcnt(0)
	v_mfma_f32_16x16x32_bf16 v[124:127], v[128:131], v[174:177], v[124:127]
	v_mfma_f32_16x16x32_bf16 v[120:123], v[146:149], v[174:177], v[120:123]
	v_mfma_f32_16x16x32_bf16 v[108:111], v[128:131], v[182:185], v[108:111]
	v_mfma_f32_16x16x32_bf16 v[104:107], v[146:149], v[182:185], v[104:107]
	v_mfma_f32_16x16x32_bf16 v[92:95], v[128:131], v[202:205], v[92:95]
	v_mfma_f32_16x16x32_bf16 v[88:91], v[146:149], v[202:205], v[88:91]
	v_mfma_f32_16x16x32_bf16 v[76:79], v[128:131], v[220:223], v[76:79]
	v_mfma_f32_16x16x32_bf16 v[72:75], v[146:149], v[220:223], v[72:75]
	v_mfma_f32_16x16x32_bf16 v[124:127], v[132:135], v[178:181], v[124:127]
	v_mfma_f32_16x16x32_bf16 v[120:123], v[150:153], v[178:181], v[120:123]
	v_mfma_f32_16x16x32_bf16 v[108:111], v[132:135], v[194:197], v[108:111]
	v_mfma_f32_16x16x32_bf16 v[104:107], v[150:153], v[194:197], v[104:107]
	v_mfma_f32_16x16x32_bf16 v[92:95], v[132:135], v[216:219], v[92:95]
	v_mfma_f32_16x16x32_bf16 v[88:91], v[150:153], v[216:219], v[88:91]
	v_mfma_f32_16x16x32_bf16 v[76:79], v[132:135], v[224:227], v[76:79]
	v_mfma_f32_16x16x32_bf16 v[72:75], v[150:153], v[224:227], v[72:75]
	s_nop 0
	s_nop 0
	v_mfma_f32_16x16x32_bf16 v[116:119], v[158:161], v[174:177], v[116:119]
	v_mfma_f32_16x16x32_bf16 v[112:115], v[166:169], v[174:177], v[112:115]
	v_mfma_f32_16x16x32_bf16 v[100:103], v[158:161], v[182:185], v[100:103]
	v_mfma_f32_16x16x32_bf16 v[96:99], v[166:169], v[182:185], v[96:99]
	v_mfma_f32_16x16x32_bf16 v[84:87], v[158:161], v[202:205], v[84:87]
	v_mfma_f32_16x16x32_bf16 v[80:83], v[166:169], v[202:205], v[80:83]
	v_mfma_f32_16x16x32_bf16 v[68:71], v[158:161], v[220:223], v[68:71]
	v_mfma_f32_16x16x32_bf16 v[64:67], v[166:169], v[220:223], v[64:67]
	v_mfma_f32_16x16x32_bf16 v[116:119], v[162:165], v[178:181], v[116:119]
	v_mfma_f32_16x16x32_bf16 v[112:115], v[170:173], v[178:181], v[112:115]
	v_mfma_f32_16x16x32_bf16 v[100:103], v[162:165], v[194:197], v[100:103]
	v_mfma_f32_16x16x32_bf16 v[96:99], v[170:173], v[194:197], v[96:99]
	v_mfma_f32_16x16x32_bf16 v[84:87], v[162:165], v[216:219], v[84:87]
	v_mfma_f32_16x16x32_bf16 v[80:83], v[170:173], v[216:219], v[80:83]
	v_mfma_f32_16x16x32_bf16 v[68:71], v[162:165], v[224:227], v[68:71]
	v_mfma_f32_16x16x32_bf16 v[64:67], v[170:173], v[224:227], v[64:67]
	s_nop 0
	s_barrier
	s_add_i32 s36, s36, s60
	v_lshl_add_u64 v[186:187], v[186:187], 0, s[62:63]
	s_mov_b32 m0, s36
	ds_read_b128 v[174:177], v157 offset:49152
	ds_read_b128 v[178:181], v157 offset:50176
	ds_read_b128 v[182:185], v157 offset:51200
	ds_read_b128 v[194:197], v157 offset:52224
	ds_read_b128 v[202:205], v157 offset:53248
	ds_read_b128 v[216:219], v157 offset:54272
	ds_read_b128 v[220:223], v157 offset:55296
	ds_read_b128 v[224:227], v157 offset:56320
	global_load_lds_dwordx4 v[186:187], off
	s_add_i32 m0, s36, 0x2000
	s_add_u32 s42, s42, 0x40080
	v_lshl_add_u64 v[186:187], v[228:229], 0, s[62:63]
	s_addc_u32 s43, s43, 0
	s_add_i32 s36, s37, s60
	global_load_lds_dwordx4 v[186:187], off
	v_lshl_add_u64 v[186:187], s[42:43], 0, v[188:189]
	s_mov_b32 m0, s36
	s_nop 0
	global_load_lds_dwordx4 v[186:187], off
	v_lshl_add_u64 v[186:187], s[42:43], 0, v[136:137]
	s_add_i32 m0, s36, 0x2000
	s_nop 0
	global_load_lds_dwordx4 v[186:187], off
	v_lshl_add_u64 v[186:187], v[230:231], 0, s[62:63]
	s_mov_b32 m0, s85
	s_nop 0
	global_load_lds_dwordx4 v[186:187], off
	v_lshl_add_u64 v[186:187], v[232:233], 0, s[62:63]
	s_mov_b32 m0, s86
	s_nop 0
	global_load_lds_dwordx4 v[186:187], off
	s_waitcnt vmcnt(8)
	s_waitcnt lgkmcnt(0)
	s_barrier
	s_nop 0
	s_waitcnt lgkmcnt(0)
	v_mfma_f32_16x16x32_bf16 v[60:63], v[128:131], v[174:177], v[60:63]
	v_mfma_f32_16x16x32_bf16 v[56:59], v[146:149], v[174:177], v[56:59]
	v_mfma_f32_16x16x32_bf16 v[44:47], v[128:131], v[182:185], v[44:47]
	v_mfma_f32_16x16x32_bf16 v[40:43], v[146:149], v[182:185], v[40:43]
	v_mfma_f32_16x16x32_bf16 v[28:31], v[128:131], v[202:205], v[28:31]
	v_mfma_f32_16x16x32_bf16 v[24:27], v[146:149], v[202:205], v[24:27]
	v_mfma_f32_16x16x32_bf16 v[12:15], v[128:131], v[220:223], v[12:15]
	v_mfma_f32_16x16x32_bf16 v[8:11], v[146:149], v[220:223], v[8:11]
	v_mfma_f32_16x16x32_bf16 v[60:63], v[132:135], v[178:181], v[60:63]
	v_mfma_f32_16x16x32_bf16 v[56:59], v[150:153], v[178:181], v[56:59]
	v_mfma_f32_16x16x32_bf16 v[44:47], v[132:135], v[194:197], v[44:47]
	v_mfma_f32_16x16x32_bf16 v[40:43], v[150:153], v[194:197], v[40:43]
	v_mfma_f32_16x16x32_bf16 v[28:31], v[132:135], v[216:219], v[28:31]
	v_mfma_f32_16x16x32_bf16 v[24:27], v[150:153], v[216:219], v[24:27]
	v_mfma_f32_16x16x32_bf16 v[12:15], v[132:135], v[224:227], v[12:15]
	v_mfma_f32_16x16x32_bf16 v[8:11], v[150:153], v[224:227], v[8:11]
	s_nop 0
	s_nop 0
	v_mfma_f32_16x16x32_bf16 v[52:55], v[158:161], v[174:177], v[52:55]
	v_mfma_f32_16x16x32_bf16 v[48:51], v[166:169], v[174:177], v[48:51]
	v_mfma_f32_16x16x32_bf16 v[36:39], v[158:161], v[182:185], v[36:39]
	v_mfma_f32_16x16x32_bf16 v[32:35], v[166:169], v[182:185], v[32:35]
	v_mfma_f32_16x16x32_bf16 v[20:23], v[158:161], v[202:205], v[20:23]
	v_mfma_f32_16x16x32_bf16 v[16:19], v[166:169], v[202:205], v[16:19]
	v_mfma_f32_16x16x32_bf16 v[4:7], v[158:161], v[220:223], v[4:7]
	v_mfma_f32_16x16x32_bf16 v[0:3], v[166:169], v[220:223], v[0:3]
	v_mfma_f32_16x16x32_bf16 v[52:55], v[162:165], v[178:181], v[52:55]
	v_mfma_f32_16x16x32_bf16 v[48:51], v[170:173], v[178:181], v[48:51]
	v_mfma_f32_16x16x32_bf16 v[36:39], v[162:165], v[194:197], v[36:39]
	v_mfma_f32_16x16x32_bf16 v[32:35], v[170:173], v[194:197], v[32:35]
	v_mfma_f32_16x16x32_bf16 v[20:23], v[162:165], v[216:219], v[20:23]
	v_mfma_f32_16x16x32_bf16 v[16:19], v[170:173], v[216:219], v[16:19]
	v_mfma_f32_16x16x32_bf16 v[4:7], v[162:165], v[224:227], v[4:7]
	v_mfma_f32_16x16x32_bf16 v[0:3], v[170:173], v[224:227], v[0:3]
	s_nop 0
	s_barrier
	s_add_u32 s40, s40, 0x100
	s_addc_u32 s41, s41, 0
	s_add_u32 s89, s89, 0x100
	s_addc_u32 s94, s94, 0
	s_cmp_ge_i32 s95, s81
	s_mov_b32 s42, s95
	s_cbranch_scc0 .LBB0_578

.LBB0_734:
	s_add_i32 s85, s48, 2
	s_add_u32 s49, s38, 0xfffc0080
	s_addc_u32 s50, s39, -1
	s_add_i32 s86, 0, 0x10000
	s_cmp_eq_u32 s70, s48
	s_cselect_b32 s51, s41, s50
	s_cselect_b32 s50, s43, s49
	v_add_u32_e32 v146, s86, v150
	s_cselect_b32 s49, s81, s84
	s_cselect_b32 s48, s82, s83
	s_add_i32 s88, 0, 0x14000
	ds_read_b128 v[138:141], v146
	ds_read_b128 v[142:145], v146 offset:1024
	ds_read_b128 v[152:155], v146 offset:2048
	ds_read_b128 v[156:159], v146 offset:3072
	v_add_u32_e32 v146, s88, v150
	ds_read_b128 v[160:163], v146
	ds_read_b128 v[164:167], v146 offset:1024
	ds_read_b128 v[168:171], v146 offset:2048
	ds_read_b128 v[172:175], v146 offset:3072
	v_lshl_add_u64 v[146:147], s[38:39], 0, v[134:135]
	s_add_i32 m0, s55, 0xc000
	ds_read_b128 v[176:179], v151
	ds_read_b128 v[180:183], v151 offset:1024
	ds_read_b128 v[184:187], v151 offset:2048
	ds_read_b128 v[194:197], v151 offset:3072
	ds_read_b128 v[202:205], v151 offset:4096
	ds_read_b128 v[216:219], v151 offset:5120
	ds_read_b128 v[220:223], v151 offset:6144
	ds_read_b128 v[224:227], v151 offset:7168
	global_load_lds_dwordx4 v[146:147], off
	v_lshl_add_u64 v[146:147], s[38:39], 0, v[136:137]
	s_add_i32 m0, s55, 0xe000
	s_nop 0
	global_load_lds_dwordx4 v[146:147], off
	s_waitcnt vmcnt(8)
	s_waitcnt lgkmcnt(0)
	s_barrier
	s_nop 0
	s_waitcnt lgkmcnt(0)
	v_mfma_f32_16x16x32_bf16 v[124:127], v[138:141], v[176:179], v[124:127]
	v_mfma_f32_16x16x32_bf16 v[120:123], v[152:155], v[176:179], v[120:123]
	v_mfma_f32_16x16x32_bf16 v[108:111], v[138:141], v[184:187], v[108:111]
	v_mfma_f32_16x16x32_bf16 v[104:107], v[152:155], v[184:187], v[104:107]
	v_mfma_f32_16x16x32_bf16 v[92:95], v[138:141], v[202:205], v[92:95]
	v_mfma_f32_16x16x32_bf16 v[88:91], v[152:155], v[202:205], v[88:91]
	v_mfma_f32_16x16x32_bf16 v[76:79], v[138:141], v[220:223], v[76:79]
	v_mfma_f32_16x16x32_bf16 v[72:75], v[152:155], v[220:223], v[72:75]
	v_mfma_f32_16x16x32_bf16 v[124:127], v[142:145], v[180:183], v[124:127]
	v_mfma_f32_16x16x32_bf16 v[120:123], v[156:159], v[180:183], v[120:123]
	v_mfma_f32_16x16x32_bf16 v[108:111], v[142:145], v[194:197], v[108:111]
	v_mfma_f32_16x16x32_bf16 v[104:107], v[156:159], v[194:197], v[104:107]
	v_mfma_f32_16x16x32_bf16 v[92:95], v[142:145], v[216:219], v[92:95]
	v_mfma_f32_16x16x32_bf16 v[88:91], v[156:159], v[216:219], v[88:91]
	v_mfma_f32_16x16x32_bf16 v[76:79], v[142:145], v[224:227], v[76:79]
	v_mfma_f32_16x16x32_bf16 v[72:75], v[156:159], v[224:227], v[72:75]
	s_nop 0
	s_nop 0
	v_mfma_f32_16x16x32_bf16 v[116:119], v[160:163], v[176:179], v[116:119]
	v_mfma_f32_16x16x32_bf16 v[112:115], v[168:171], v[176:179], v[112:115]
	v_mfma_f32_16x16x32_bf16 v[100:103], v[160:163], v[184:187], v[100:103]
	v_mfma_f32_16x16x32_bf16 v[96:99], v[168:171], v[184:187], v[96:99]
	v_mfma_f32_16x16x32_bf16 v[84:87], v[160:163], v[202:205], v[84:87]
	v_mfma_f32_16x16x32_bf16 v[80:83], v[168:171], v[202:205], v[80:83]
	v_mfma_f32_16x16x32_bf16 v[68:71], v[160:163], v[220:223], v[68:71]
	v_mfma_f32_16x16x32_bf16 v[64:67], v[168:171], v[220:223], v[64:67]
	v_mfma_f32_16x16x32_bf16 v[116:119], v[164:167], v[180:183], v[116:119]
	v_mfma_f32_16x16x32_bf16 v[112:115], v[172:175], v[180:183], v[112:115]
	v_mfma_f32_16x16x32_bf16 v[100:103], v[164:167], v[194:197], v[100:103]
	v_mfma_f32_16x16x32_bf16 v[96:99], v[172:175], v[194:197], v[96:99]
	v_mfma_f32_16x16x32_bf16 v[84:87], v[164:167], v[216:219], v[84:87]
	v_mfma_f32_16x16x32_bf16 v[80:83], v[172:175], v[216:219], v[80:83]
	v_mfma_f32_16x16x32_bf16 v[68:71], v[164:167], v[224:227], v[68:71]
	v_mfma_f32_16x16x32_bf16 v[64:67], v[172:175], v[224:227], v[64:67]
	s_nop 0
	s_barrier
	s_add_i32 s86, s86, s54
	v_lshl_add_u64 v[146:147], s[48:49], 0, v[188:189]
	s_mov_b32 m0, s86
	ds_read_b128 v[176:179], v151 offset:16384
	ds_read_b128 v[180:183], v151 offset:17408
	ds_read_b128 v[184:187], v151 offset:18432
	ds_read_b128 v[194:197], v151 offset:19456
	ds_read_b128 v[202:205], v151 offset:20480
	ds_read_b128 v[216:219], v151 offset:21504
	ds_read_b128 v[220:223], v151 offset:22528
	ds_read_b128 v[224:227], v151 offset:23552
	global_load_lds_dwordx4 v[146:147], off
	s_add_i32 m0, s86, 0x2000
	s_add_u32 s86, s48, 0x40000
	v_lshl_add_u64 v[228:229], s[48:49], 0, v[128:129]
	s_addc_u32 s87, s49, 0
	s_add_i32 s88, s88, s54
	global_load_lds_dwordx4 v[228:229], off
	v_lshl_add_u64 v[230:231], s[86:87], 0, v[188:189]
	s_mov_b32 m0, s88
	v_lshl_add_u64 v[232:233], s[50:51], 0, v[130:131]
	global_load_lds_dwordx4 v[230:231], off
	v_lshl_add_u64 v[230:231], s[86:87], 0, v[128:129]
	s_add_i32 m0, s88, 0x2000
	s_nop 0
	global_load_lds_dwordx4 v[230:231], off
	v_lshl_add_u64 v[230:231], s[50:51], 0, v[132:133]
	s_mov_b32 m0, s55
	s_nop 0
	global_load_lds_dwordx4 v[230:231], off
	s_mov_b32 m0, s56
	s_nop 0
	global_load_lds_dwordx4 v[232:233], off
	s_waitcnt vmcnt(8)
	s_waitcnt lgkmcnt(0)
	s_barrier
	s_nop 0
	s_waitcnt lgkmcnt(0)
	v_mfma_f32_16x16x32_bf16 v[60:63], v[138:141], v[176:179], v[60:63]
	v_mfma_f32_16x16x32_bf16 v[56:59], v[152:155], v[176:179], v[56:59]
	v_mfma_f32_16x16x32_bf16 v[44:47], v[138:141], v[184:187], v[44:47]
	v_mfma_f32_16x16x32_bf16 v[40:43], v[152:155], v[184:187], v[40:43]
	v_mfma_f32_16x16x32_bf16 v[28:31], v[138:141], v[202:205], v[28:31]
	v_mfma_f32_16x16x32_bf16 v[24:27], v[152:155], v[202:205], v[24:27]
	v_mfma_f32_16x16x32_bf16 v[12:15], v[138:141], v[220:223], v[12:15]
	v_mfma_f32_16x16x32_bf16 v[8:11], v[152:155], v[220:223], v[8:11]
	v_mfma_f32_16x16x32_bf16 v[60:63], v[142:145], v[180:183], v[60:63]
	v_mfma_f32_16x16x32_bf16 v[56:59], v[156:159], v[180:183], v[56:59]
	v_mfma_f32_16x16x32_bf16 v[44:47], v[142:145], v[194:197], v[44:47]
	v_mfma_f32_16x16x32_bf16 v[40:43], v[156:159], v[194:197], v[40:43]
	v_mfma_f32_16x16x32_bf16 v[28:31], v[142:145], v[216:219], v[28:31]
	v_mfma_f32_16x16x32_bf16 v[24:27], v[156:159], v[216:219], v[24:27]
	v_mfma_f32_16x16x32_bf16 v[12:15], v[142:145], v[224:227], v[12:15]
	v_mfma_f32_16x16x32_bf16 v[8:11], v[156:159], v[224:227], v[8:11]
	s_nop 0
	s_nop 0
	v_mfma_f32_16x16x32_bf16 v[52:55], v[160:163], v[176:179], v[52:55]
	v_mfma_f32_16x16x32_bf16 v[48:51], v[168:171], v[176:179], v[48:51]
	v_mfma_f32_16x16x32_bf16 v[36:39], v[160:163], v[184:187], v[36:39]
	v_mfma_f32_16x16x32_bf16 v[32:35], v[168:171], v[184:187], v[32:35]
	v_mfma_f32_16x16x32_bf16 v[20:23], v[160:163], v[202:205], v[20:23]
	v_mfma_f32_16x16x32_bf16 v[16:19], v[168:171], v[202:205], v[16:19]
	v_mfma_f32_16x16x32_bf16 v[4:7], v[160:163], v[220:223], v[4:7]
	v_mfma_f32_16x16x32_bf16 v[0:3], v[168:171], v[220:223], v[0:3]
	v_mfma_f32_16x16x32_bf16 v[52:55], v[164:167], v[180:183], v[52:55]
	v_mfma_f32_16x16x32_bf16 v[48:51], v[172:175], v[180:183], v[48:51]
	v_mfma_f32_16x16x32_bf16 v[36:39], v[164:167], v[194:197], v[36:39]
	v_mfma_f32_16x16x32_bf16 v[32:35], v[172:175], v[194:197], v[32:35]
	v_mfma_f32_16x16x32_bf16 v[20:23], v[164:167], v[216:219], v[20:23]
	v_mfma_f32_16x16x32_bf16 v[16:19], v[172:175], v[216:219], v[16:19]
	v_mfma_f32_16x16x32_bf16 v[4:7], v[164:167], v[224:227], v[4:7]
	v_mfma_f32_16x16x32_bf16 v[0:3], v[172:175], v[224:227], v[0:3]
	s_nop 0
	s_barrier
	s_add_i32 s86, 0, 0x18000
	s_add_i32 s87, 0, 0x1c000
	v_add_u32_e32 v156, s86, v150
	v_add_u32_e32 v172, s87, v150
	ds_read_b128 v[138:141], v156
	ds_read_b128 v[142:145], v156 offset:1024
	ds_read_b128 v[152:155], v156 offset:2048
	ds_read_b128 v[156:159], v156 offset:3072
	ds_read_b128 v[160:163], v172
	ds_read_b128 v[164:167], v172 offset:1024
	ds_read_b128 v[168:171], v172 offset:2048
	ds_read_b128 v[172:175], v172 offset:3072
	s_add_u32 s50, s50, 0x40000
	s_addc_u32 s51, s51, 0
	s_mov_b32 m0, s57
	v_lshl_add_u64 v[234:235], s[50:51], 0, v[132:133]
	ds_read_b128 v[176:179], v151 offset:32768
	ds_read_b128 v[180:183], v151 offset:33792
	ds_read_b128 v[184:187], v151 offset:34816
	ds_read_b128 v[194:197], v151 offset:35840
	ds_read_b128 v[202:205], v151 offset:36864
	ds_read_b128 v[216:219], v151 offset:37888
	ds_read_b128 v[220:223], v151 offset:38912
	ds_read_b128 v[224:227], v151 offset:39936
	global_load_lds_dwordx4 v[234:235], off
	v_lshl_add_u64 v[234:235], s[50:51], 0, v[130:131]
	s_mov_b32 m0, s58
	s_nop 0
	global_load_lds_dwordx4 v[234:235], off
	s_waitcnt vmcnt(8)
	s_waitcnt lgkmcnt(0)
	s_barrier
	s_nop 0
	s_waitcnt lgkmcnt(0)
	v_mfma_f32_16x16x32_bf16 v[124:127], v[138:141], v[176:179], v[124:127]
	v_mfma_f32_16x16x32_bf16 v[120:123], v[152:155], v[176:179], v[120:123]
	v_mfma_f32_16x16x32_bf16 v[108:111], v[138:141], v[184:187], v[108:111]
	v_mfma_f32_16x16x32_bf16 v[104:107], v[152:155], v[184:187], v[104:107]
	v_mfma_f32_16x16x32_bf16 v[92:95], v[138:141], v[202:205], v[92:95]
	v_mfma_f32_16x16x32_bf16 v[88:91], v[152:155], v[202:205], v[88:91]
	v_mfma_f32_16x16x32_bf16 v[76:79], v[138:141], v[220:223], v[76:79]
	v_mfma_f32_16x16x32_bf16 v[72:75], v[152:155], v[220:223], v[72:75]
	v_mfma_f32_16x16x32_bf16 v[124:127], v[142:145], v[180:183], v[124:127]
	v_mfma_f32_16x16x32_bf16 v[120:123], v[156:159], v[180:183], v[120:123]
	v_mfma_f32_16x16x32_bf16 v[108:111], v[142:145], v[194:197], v[108:111]
	v_mfma_f32_16x16x32_bf16 v[104:107], v[156:159], v[194:197], v[104:107]
	v_mfma_f32_16x16x32_bf16 v[92:95], v[142:145], v[216:219], v[92:95]
	v_mfma_f32_16x16x32_bf16 v[88:91], v[156:159], v[216:219], v[88:91]
	v_mfma_f32_16x16x32_bf16 v[76:79], v[142:145], v[224:227], v[76:79]
	v_mfma_f32_16x16x32_bf16 v[72:75], v[156:159], v[224:227], v[72:75]
	s_nop 0
	s_nop 0
	v_mfma_f32_16x16x32_bf16 v[116:119], v[160:163], v[176:179], v[116:119]
	v_mfma_f32_16x16x32_bf16 v[112:115], v[168:171], v[176:179], v[112:115]
	v_mfma_f32_16x16x32_bf16 v[100:103], v[160:163], v[184:187], v[100:103]
	v_mfma_f32_16x16x32_bf16 v[96:99], v[168:171], v[184:187], v[96:99]
	v_mfma_f32_16x16x32_bf16 v[84:87], v[160:163], v[202:205], v[84:87]
	v_mfma_f32_16x16x32_bf16 v[80:83], v[168:171], v[202:205], v[80:83]
	v_mfma_f32_16x16x32_bf16 v[68:71], v[160:163], v[220:223], v[68:71]
	v_mfma_f32_16x16x32_bf16 v[64:67], v[168:171], v[220:223], v[64:67]
	v_mfma_f32_16x16x32_bf16 v[116:119], v[164:167], v[180:183], v[116:119]
	v_mfma_f32_16x16x32_bf16 v[112:115], v[172:175], v[180:183], v[112:115]
	v_mfma_f32_16x16x32_bf16 v[100:103], v[164:167], v[194:197], v[100:103]
	v_mfma_f32_16x16x32_bf16 v[96:99], v[172:175], v[194:197], v[96:99]
	v_mfma_f32_16x16x32_bf16 v[84:87], v[164:167], v[216:219], v[84:87]
	v_mfma_f32_16x16x32_bf16 v[80:83], v[172:175], v[216:219], v[80:83]
	v_mfma_f32_16x16x32_bf16 v[68:71], v[164:167], v[224:227], v[68:71]
	v_mfma_f32_16x16x32_bf16 v[64:67], v[172:175], v[224:227], v[64:67]
	s_nop 0
	s_barrier
	s_add_i32 s50, s86, s54
	v_lshl_add_u64 v[146:147], v[146:147], 0, s[62:63]
	s_mov_b32 m0, s50
	ds_read_b128 v[176:179], v151 offset:49152
	ds_read_b128 v[180:183], v151 offset:50176
	ds_read_b128 v[184:187], v151 offset:51200
	ds_read_b128 v[194:197], v151 offset:52224
	ds_read_b128 v[202:205], v151 offset:53248
	ds_read_b128 v[216:219], v151 offset:54272
	ds_read_b128 v[220:223], v151 offset:55296
	ds_read_b128 v[224:227], v151 offset:56320
	global_load_lds_dwordx4 v[146:147], off
	s_add_i32 m0, s50, 0x2000
	s_add_u32 s48, s48, 0x40080
	v_lshl_add_u64 v[146:147], v[228:229], 0, s[62:63]
	s_addc_u32 s49, s49, 0
	s_add_i32 s50, s87, s54
	global_load_lds_dwordx4 v[146:147], off
	v_lshl_add_u64 v[146:147], s[48:49], 0, v[188:189]
	s_mov_b32 m0, s50
	s_nop 0
	global_load_lds_dwordx4 v[146:147], off
	v_lshl_add_u64 v[146:147], s[48:49], 0, v[128:129]
	s_add_i32 m0, s50, 0x2000
	s_nop 0
	global_load_lds_dwordx4 v[146:147], off
	v_lshl_add_u64 v[146:147], v[230:231], 0, s[62:63]
	s_mov_b32 m0, s67
	s_nop 0
	global_load_lds_dwordx4 v[146:147], off
	v_lshl_add_u64 v[146:147], v[232:233], 0, s[62:63]
	s_mov_b32 m0, s69
	s_nop 0
	global_load_lds_dwordx4 v[146:147], off
	s_waitcnt vmcnt(8)
	s_waitcnt lgkmcnt(0)
	s_barrier
	s_nop 0
	s_waitcnt lgkmcnt(0)
	v_mfma_f32_16x16x32_bf16 v[60:63], v[138:141], v[176:179], v[60:63]
	v_mfma_f32_16x16x32_bf16 v[56:59], v[152:155], v[176:179], v[56:59]
	v_mfma_f32_16x16x32_bf16 v[44:47], v[138:141], v[184:187], v[44:47]
	v_mfma_f32_16x16x32_bf16 v[40:43], v[152:155], v[184:187], v[40:43]
	v_mfma_f32_16x16x32_bf16 v[28:31], v[138:141], v[202:205], v[28:31]
	v_mfma_f32_16x16x32_bf16 v[24:27], v[152:155], v[202:205], v[24:27]
	v_mfma_f32_16x16x32_bf16 v[12:15], v[138:141], v[220:223], v[12:15]
	v_mfma_f32_16x16x32_bf16 v[8:11], v[152:155], v[220:223], v[8:11]
	v_mfma_f32_16x16x32_bf16 v[60:63], v[142:145], v[180:183], v[60:63]
	v_mfma_f32_16x16x32_bf16 v[56:59], v[156:159], v[180:183], v[56:59]
	v_mfma_f32_16x16x32_bf16 v[44:47], v[142:145], v[194:197], v[44:47]
	v_mfma_f32_16x16x32_bf16 v[40:43], v[156:159], v[194:197], v[40:43]
	v_mfma_f32_16x16x32_bf16 v[28:31], v[142:145], v[216:219], v[28:31]
	v_mfma_f32_16x16x32_bf16 v[24:27], v[156:159], v[216:219], v[24:27]
	v_mfma_f32_16x16x32_bf16 v[12:15], v[142:145], v[224:227], v[12:15]
	v_mfma_f32_16x16x32_bf16 v[8:11], v[156:159], v[224:227], v[8:11]
	s_nop 0
	s_nop 0
	v_mfma_f32_16x16x32_bf16 v[52:55], v[160:163], v[176:179], v[52:55]
	v_mfma_f32_16x16x32_bf16 v[48:51], v[168:171], v[176:179], v[48:51]
	v_mfma_f32_16x16x32_bf16 v[36:39], v[160:163], v[184:187], v[36:39]
	v_mfma_f32_16x16x32_bf16 v[32:35], v[168:171], v[184:187], v[32:35]
	v_mfma_f32_16x16x32_bf16 v[20:23], v[160:163], v[202:205], v[20:23]
	v_mfma_f32_16x16x32_bf16 v[16:19], v[168:171], v[202:205], v[16:19]
	v_mfma_f32_16x16x32_bf16 v[4:7], v[160:163], v[220:223], v[4:7]
	v_mfma_f32_16x16x32_bf16 v[0:3], v[168:171], v[220:223], v[0:3]
	v_mfma_f32_16x16x32_bf16 v[52:55], v[164:167], v[180:183], v[52:55]
	v_mfma_f32_16x16x32_bf16 v[48:51], v[172:175], v[180:183], v[48:51]
	v_mfma_f32_16x16x32_bf16 v[36:39], v[164:167], v[194:197], v[36:39]
	v_mfma_f32_16x16x32_bf16 v[32:35], v[172:175], v[194:197], v[32:35]
	v_mfma_f32_16x16x32_bf16 v[20:23], v[164:167], v[216:219], v[20:23]
	v_mfma_f32_16x16x32_bf16 v[16:19], v[172:175], v[216:219], v[16:19]
	v_mfma_f32_16x16x32_bf16 v[4:7], v[164:167], v[224:227], v[4:7]
	v_mfma_f32_16x16x32_bf16 v[0:3], v[172:175], v[224:227], v[0:3]
	s_nop 0
	s_barrier
	s_add_u32 s38, s38, 0x100
	s_addc_u32 s39, s39, 0
	s_add_u32 s83, s83, 0x100
	s_addc_u32 s84, s84, 0
	s_cmp_ge_i32 s85, s60
	s_mov_b32 s48, s85
	s_cbranch_scc0 .LBB0_734
	s_mov_b64 s[88:89], 0x8000
